# GEMM loop: 3/5 DMA split (only second piece of A0 pairs deferred to next LS1), LS2 vmcnt 7
# speedup vs baseline: 1.0064x; 1.0064x over previous
.LBB0_176:
	v_add_u32_e32 v130, 0x10000, v243
	v_add_u32_e32 v142, 0x14000, v243
	ds_read_b128 v[146:149], v130
	ds_read_b128 v[150:153], v130 offset:1024
	ds_read_b128 v[154:157], v130 offset:2048
	ds_read_b128 v[158:161], v130 offset:3072
	ds_read_b128 v[130:133], v142
	ds_read_b128 v[134:137], v142 offset:1024
	ds_read_b128 v[138:141], v142 offset:2048
	ds_read_b128 v[142:145], v142 offset:3072
	v_lshl_add_u64 v[246:247], v[234:235], 0, s[80:81]
	s_add_i32 m0, s8, 0xc000
	s_waitcnt lgkmcnt(0)
	ds_read_b128 v[174:177], v244
	ds_read_b128 v[190:193], v244 offset:1024
	ds_read_b128 v[170:173], v244 offset:2048
	ds_read_b128 v[186:189], v244 offset:3072
	ds_read_b128 v[166:169], v244 offset:4096
	ds_read_b128 v[182:185], v244 offset:5120
	ds_read_b128 v[162:165], v244 offset:6144
	ds_read_b128 v[178:181], v244 offset:7168
	s_mov_b32 m0, s67
	s_nop 0
	global_load_lds_dwordx4 v196, s[100:101]
	s_add_i32 m0, s8, 0xc000
	s_nop 0
	global_load_lds_dwordx4 v[246:247], off
	v_lshl_add_u64 v[246:247], v[236:237], 0, s[80:81]
	s_add_i32 m0, s8, 0xe000
	s_nop 0
	global_load_lds_dwordx4 v[246:247], off
	s_waitcnt vmcnt(8)
	s_waitcnt lgkmcnt(0)
	s_barrier
	s_setprio 1
	s_waitcnt lgkmcnt(0)
	v_mfma_f32_16x16x32_bf16 v[118:121], v[146:149], v[174:177], v[118:121]
	v_mfma_f32_16x16x32_bf16 v[126:129], v[154:157], v[174:177], v[126:129]
	v_mfma_f32_16x16x32_bf16 v[102:105], v[146:149], v[170:173], v[102:105]
	v_mfma_f32_16x16x32_bf16 v[110:113], v[154:157], v[170:173], v[110:113]
	v_mfma_f32_16x16x32_bf16 v[86:89], v[146:149], v[166:169], v[86:89]
	v_mfma_f32_16x16x32_bf16 v[94:97], v[154:157], v[166:169], v[94:97]
	v_mfma_f32_16x16x32_bf16 v[70:73], v[146:149], v[162:165], v[70:73]
	v_mfma_f32_16x16x32_bf16 v[78:81], v[154:157], v[162:165], v[78:81]
	v_mfma_f32_16x16x32_bf16 v[118:121], v[150:153], v[190:193], v[118:121]
	v_mfma_f32_16x16x32_bf16 v[126:129], v[158:161], v[190:193], v[126:129]
	v_mfma_f32_16x16x32_bf16 v[102:105], v[150:153], v[186:189], v[102:105]
	v_mfma_f32_16x16x32_bf16 v[110:113], v[158:161], v[186:189], v[110:113]
	v_mfma_f32_16x16x32_bf16 v[86:89], v[150:153], v[182:185], v[86:89]
	v_mfma_f32_16x16x32_bf16 v[94:97], v[158:161], v[182:185], v[94:97]
	v_mfma_f32_16x16x32_bf16 v[70:73], v[150:153], v[178:181], v[70:73]
	v_mfma_f32_16x16x32_bf16 v[78:81], v[158:161], v[178:181], v[78:81]
	s_setprio 0
	s_setprio 1
	v_mfma_f32_16x16x32_bf16 v[122:125], v[130:133], v[174:177], v[122:125]
	v_mfma_f32_16x16x32_bf16 v[114:117], v[138:141], v[174:177], v[114:117]
	v_mfma_f32_16x16x32_bf16 v[106:109], v[130:133], v[170:173], v[106:109]
	v_mfma_f32_16x16x32_bf16 v[98:101], v[138:141], v[170:173], v[98:101]
	v_mfma_f32_16x16x32_bf16 v[90:93], v[130:133], v[166:169], v[90:93]
	v_mfma_f32_16x16x32_bf16 v[82:85], v[138:141], v[166:169], v[82:85]
	v_mfma_f32_16x16x32_bf16 v[74:77], v[130:133], v[162:165], v[74:77]
	v_mfma_f32_16x16x32_bf16 v[66:69], v[138:141], v[162:165], v[66:69]
	v_mfma_f32_16x16x32_bf16 v[122:125], v[134:137], v[190:193], v[122:125]
	v_mfma_f32_16x16x32_bf16 v[114:117], v[142:145], v[190:193], v[114:117]
	v_mfma_f32_16x16x32_bf16 v[106:109], v[134:137], v[186:189], v[106:109]
	v_mfma_f32_16x16x32_bf16 v[98:101], v[142:145], v[186:189], v[98:101]
	v_mfma_f32_16x16x32_bf16 v[90:93], v[134:137], v[182:185], v[90:93]
	v_mfma_f32_16x16x32_bf16 v[82:85], v[142:145], v[182:185], v[82:85]
	v_mfma_f32_16x16x32_bf16 v[74:77], v[134:137], v[178:181], v[74:77]
	v_mfma_f32_16x16x32_bf16 v[66:69], v[142:145], v[178:181], v[66:69]
	s_setprio 0
	s_barrier
	v_cndmask_b32_e64 v246, 0, 1, s[50:51]
	v_cmp_ne_u32_e64 s[48:49], 1, v246
	s_andn2_b64 vcc, exec, s[50:51]
	s_cbranch_vccnz .LBB0_178
	ds_read_b128 v[174:177], v244 offset:16384
	ds_read_b128 v[190:193], v244 offset:17408
	ds_read_b128 v[170:173], v244 offset:18432
	ds_read_b128 v[186:189], v244 offset:19456
	ds_read_b128 v[166:169], v244 offset:20480
	ds_read_b128 v[182:185], v244 offset:21504
	ds_read_b128 v[162:165], v244 offset:22528
	ds_read_b128 v[178:181], v244 offset:23552
.LBB0_178:
	s_add_u32 s82, s0, s80
	s_addc_u32 s83, s1, s81
	s_add_u32 s84, s82, 0x460000
	s_addc_u32 s85, s83, 0
	s_cmp_eq_u32 s80, 0x41a0000
	s_cselect_b64 s[86:87], -1, 0
	s_and_b64 s[82:83], s[86:87], exec
	s_cselect_b32 s83, s71, s97
	s_cselect_b32 s82, s73, s79
	s_mov_b32 m0, s9
	s_cselect_b32 s85, s22, s85
	s_cselect_b32 s84, s69, s84
	v_lshl_add_u64 v[246:247], s[82:83], 0, v[194:195]
	s_add_u32 vcc_lo, s82, 0x4000
	global_load_lds_dwordx4 v[246:247], off
	v_lshl_add_u64 v[246:247], s[82:83], 0, v[196:197]
	s_mov_b32 m0, s10
	s_addc_u32 vcc_hi, s83, 0
	global_load_lds_dwordx4 v[246:247], off
	v_lshl_add_u64 v[246:247], vcc, 0, v[194:195]
	s_mov_b32 m0, s11
	s_nop 0
	global_load_lds_dwordx4 v[246:247], off
	v_lshl_add_u64 v[246:247], vcc, 0, v[196:197]
	s_mov_b32 m0, s12
	s_and_b64 vcc, exec, s[48:49]
	global_load_lds_dwordx4 v[246:247], off
	v_lshl_add_u64 v[246:247], s[84:85], 0, v[194:195]
	s_mov_b32 m0, s8
	s_nop 0
	global_load_lds_dwordx4 v[246:247], off
	s_mov_b64 s[98:99], s[84:85]
	s_waitcnt vmcnt(7)
	s_waitcnt lgkmcnt(0)
	s_barrier
	s_cbranch_vccnz .LBB0_180
	s_setprio 1
	s_waitcnt lgkmcnt(0)
	v_mfma_f32_16x16x32_bf16 v[54:57], v[146:149], v[174:177], v[54:57]
	v_mfma_f32_16x16x32_bf16 v[62:65], v[154:157], v[174:177], v[62:65]
	v_mfma_f32_16x16x32_bf16 v[38:41], v[146:149], v[170:173], v[38:41]
	v_mfma_f32_16x16x32_bf16 v[46:49], v[154:157], v[170:173], v[46:49]
	v_mfma_f32_16x16x32_bf16 v[22:25], v[146:149], v[166:169], v[22:25]
	v_mfma_f32_16x16x32_bf16 v[30:33], v[154:157], v[166:169], v[30:33]
	v_mfma_f32_16x16x32_bf16 v[10:13], v[146:149], v[162:165], v[10:13]
	v_mfma_f32_16x16x32_bf16 v[14:17], v[154:157], v[162:165], v[14:17]
	v_mfma_f32_16x16x32_bf16 v[54:57], v[150:153], v[190:193], v[54:57]
	v_mfma_f32_16x16x32_bf16 v[62:65], v[158:161], v[190:193], v[62:65]
	v_mfma_f32_16x16x32_bf16 v[38:41], v[150:153], v[186:189], v[38:41]
	v_mfma_f32_16x16x32_bf16 v[46:49], v[158:161], v[186:189], v[46:49]
	v_mfma_f32_16x16x32_bf16 v[22:25], v[150:153], v[182:185], v[22:25]
	v_mfma_f32_16x16x32_bf16 v[30:33], v[158:161], v[182:185], v[30:33]
	v_mfma_f32_16x16x32_bf16 v[10:13], v[150:153], v[178:181], v[10:13]
	v_mfma_f32_16x16x32_bf16 v[14:17], v[158:161], v[178:181], v[14:17]
	s_setprio 0
	s_setprio 1
	v_mfma_f32_16x16x32_bf16 v[58:61], v[130:133], v[174:177], v[58:61]
	v_mfma_f32_16x16x32_bf16 v[50:53], v[138:141], v[174:177], v[50:53]
	v_mfma_f32_16x16x32_bf16 v[42:45], v[130:133], v[170:173], v[42:45]
	v_mfma_f32_16x16x32_bf16 v[34:37], v[138:141], v[170:173], v[34:37]
	v_mfma_f32_16x16x32_bf16 v[26:29], v[130:133], v[166:169], v[26:29]
	v_mfma_f32_16x16x32_bf16 v[18:21], v[138:141], v[166:169], v[18:21]
	v_mfma_f32_16x16x32_bf16 v[6:9], v[130:133], v[162:165], v[6:9]
	v_mfma_f32_16x16x32_bf16 v[2:5], v[138:141], v[162:165], v[2:5]
	v_mfma_f32_16x16x32_bf16 v[58:61], v[134:137], v[190:193], v[58:61]
	v_mfma_f32_16x16x32_bf16 v[50:53], v[142:145], v[190:193], v[50:53]
	v_mfma_f32_16x16x32_bf16 v[42:45], v[134:137], v[186:189], v[42:45]
	v_mfma_f32_16x16x32_bf16 v[34:37], v[142:145], v[186:189], v[34:37]
	v_mfma_f32_16x16x32_bf16 v[26:29], v[134:137], v[182:185], v[26:29]
	v_mfma_f32_16x16x32_bf16 v[18:21], v[142:145], v[182:185], v[18:21]
	v_mfma_f32_16x16x32_bf16 v[6:9], v[134:137], v[178:181], v[6:9]
	v_mfma_f32_16x16x32_bf16 v[2:5], v[142:145], v[178:181], v[2:5]
	s_setprio 0
.LBB0_180:
	s_and_b64 vcc, s[46:47], s[86:87]
	v_cndmask_b32_e64 v131, v233, 0, vcc
	v_cndmask_b32_e32 v130, v232, v198, vcc
	v_lshl_add_u64 v[246:247], s[84:85], 0, v[130:131]
	s_barrier
	v_add_u32_e32 v130, 0x18000, v243
	v_add_u32_e32 v142, 0x1c000, v243
	ds_read_b128 v[146:149], v130
	ds_read_b128 v[150:153], v130 offset:1024
	ds_read_b128 v[154:157], v130 offset:2048
	ds_read_b128 v[158:161], v130 offset:3072
	ds_read_b128 v[130:133], v142
	ds_read_b128 v[134:137], v142 offset:1024
	ds_read_b128 v[138:141], v142 offset:2048
	ds_read_b128 v[142:145], v142 offset:3072
	s_mov_b32 m0, s14
	v_lshl_add_u64 v[248:249], v[246:247], 0, v[194:195]
	s_waitcnt lgkmcnt(0)
	ds_read_b128 v[174:177], v244 offset:32768
	ds_read_b128 v[190:193], v244 offset:33792
	ds_read_b128 v[170:173], v244 offset:34816
	ds_read_b128 v[186:189], v244 offset:35840
	ds_read_b128 v[166:169], v244 offset:36864
	ds_read_b128 v[182:185], v244 offset:37888
	ds_read_b128 v[162:165], v244 offset:38912
	ds_read_b128 v[178:181], v244 offset:39936
	s_mov_b32 m0, s13
	s_nop 0
	global_load_lds_dwordx4 v196, s[98:99]
	s_mov_b32 m0, s14
	s_nop 0
	global_load_lds_dwordx4 v[248:249], off
	v_lshl_add_u64 v[246:247], v[246:247], 0, v[196:197]
	s_mov_b32 m0, s15
	s_nop 0
	global_load_lds_dwordx4 v[246:247], off
	s_waitcnt vmcnt(8)
	s_waitcnt lgkmcnt(0)
	s_barrier
	s_setprio 1
	s_waitcnt lgkmcnt(0)
	v_mfma_f32_16x16x32_bf16 v[118:121], v[146:149], v[174:177], v[118:121]
	v_mfma_f32_16x16x32_bf16 v[126:129], v[154:157], v[174:177], v[126:129]
	v_mfma_f32_16x16x32_bf16 v[102:105], v[146:149], v[170:173], v[102:105]
	v_mfma_f32_16x16x32_bf16 v[110:113], v[154:157], v[170:173], v[110:113]
	v_mfma_f32_16x16x32_bf16 v[86:89], v[146:149], v[166:169], v[86:89]
	v_mfma_f32_16x16x32_bf16 v[94:97], v[154:157], v[166:169], v[94:97]
	v_mfma_f32_16x16x32_bf16 v[70:73], v[146:149], v[162:165], v[70:73]
	v_mfma_f32_16x16x32_bf16 v[78:81], v[154:157], v[162:165], v[78:81]
	v_mfma_f32_16x16x32_bf16 v[118:121], v[150:153], v[190:193], v[118:121]
	v_mfma_f32_16x16x32_bf16 v[126:129], v[158:161], v[190:193], v[126:129]
	v_mfma_f32_16x16x32_bf16 v[102:105], v[150:153], v[186:189], v[102:105]
	v_mfma_f32_16x16x32_bf16 v[110:113], v[158:161], v[186:189], v[110:113]
	v_mfma_f32_16x16x32_bf16 v[86:89], v[150:153], v[182:185], v[86:89]
	v_mfma_f32_16x16x32_bf16 v[94:97], v[158:161], v[182:185], v[94:97]
	v_mfma_f32_16x16x32_bf16 v[70:73], v[150:153], v[178:181], v[70:73]
	v_mfma_f32_16x16x32_bf16 v[78:81], v[158:161], v[178:181], v[78:81]
	s_setprio 0
	s_setprio 1
	v_mfma_f32_16x16x32_bf16 v[122:125], v[130:133], v[174:177], v[122:125]
	v_mfma_f32_16x16x32_bf16 v[114:117], v[138:141], v[174:177], v[114:117]
	v_mfma_f32_16x16x32_bf16 v[106:109], v[130:133], v[170:173], v[106:109]
	v_mfma_f32_16x16x32_bf16 v[98:101], v[138:141], v[170:173], v[98:101]
	v_mfma_f32_16x16x32_bf16 v[90:93], v[130:133], v[166:169], v[90:93]
	v_mfma_f32_16x16x32_bf16 v[82:85], v[138:141], v[166:169], v[82:85]
	v_mfma_f32_16x16x32_bf16 v[74:77], v[130:133], v[162:165], v[74:77]
	v_mfma_f32_16x16x32_bf16 v[66:69], v[138:141], v[162:165], v[66:69]
	v_mfma_f32_16x16x32_bf16 v[122:125], v[134:137], v[190:193], v[122:125]
	v_mfma_f32_16x16x32_bf16 v[114:117], v[142:145], v[190:193], v[114:117]
	v_mfma_f32_16x16x32_bf16 v[106:109], v[134:137], v[186:189], v[106:109]
	v_mfma_f32_16x16x32_bf16 v[98:101], v[142:145], v[186:189], v[98:101]
	v_mfma_f32_16x16x32_bf16 v[90:93], v[134:137], v[182:185], v[90:93]
	v_mfma_f32_16x16x32_bf16 v[82:85], v[142:145], v[182:185], v[82:85]
	v_mfma_f32_16x16x32_bf16 v[74:77], v[134:137], v[178:181], v[74:77]
	v_mfma_f32_16x16x32_bf16 v[66:69], v[142:145], v[178:181], v[66:69]
	s_setprio 0
	s_barrier
	s_and_b64 vcc, exec, s[48:49]
	s_cbranch_vccnz .LBB0_182
	ds_read_b128 v[174:177], v244 offset:49152
	ds_read_b128 v[190:193], v244 offset:50176
	ds_read_b128 v[170:173], v244 offset:51200
	ds_read_b128 v[186:189], v244 offset:52224
	ds_read_b128 v[166:169], v244 offset:53248
	ds_read_b128 v[182:185], v244 offset:54272
	ds_read_b128 v[162:165], v244 offset:55296
	ds_read_b128 v[178:181], v244 offset:56320
.LBB0_182:
	s_add_u32 s86, s82, 0x120000
	s_addc_u32 s87, s83, 0
	s_add_u32 s84, s84, 0x230000
	s_addc_u32 s85, s85, 0
	s_mov_b32 m0, s17
	v_lshl_add_u64 v[246:247], s[86:87], 0, v[194:195]
	s_add_u32 s82, s82, 0x124000
	global_load_lds_dwordx4 v[246:247], off
	v_lshl_add_u64 v[246:247], s[86:87], 0, v[196:197]
	s_mov_b32 m0, s54
	s_addc_u32 s83, s83, 0
	global_load_lds_dwordx4 v[246:247], off
	v_lshl_add_u64 v[246:247], s[82:83], 0, v[194:195]
	s_mov_b32 m0, s89
	s_and_b64 vcc, exec, s[48:49]
	global_load_lds_dwordx4 v[246:247], off
	v_lshl_add_u64 v[246:247], s[82:83], 0, v[196:197]
	s_mov_b32 m0, s90
	s_nop 0
	global_load_lds_dwordx4 v[246:247], off
	v_lshl_add_u64 v[246:247], s[84:85], 0, v[194:195]
	s_mov_b32 m0, s55
	s_nop 0
	global_load_lds_dwordx4 v[246:247], off
	s_mov_b64 s[100:101], s[84:85]
	s_waitcnt vmcnt(7)
	s_waitcnt lgkmcnt(0)
	s_barrier
	s_cbranch_vccnz .LBB0_175
	s_setprio 1
	s_waitcnt lgkmcnt(0)
	v_mfma_f32_16x16x32_bf16 v[54:57], v[146:149], v[174:177], v[54:57]
	v_mfma_f32_16x16x32_bf16 v[62:65], v[154:157], v[174:177], v[62:65]
	v_mfma_f32_16x16x32_bf16 v[38:41], v[146:149], v[170:173], v[38:41]
	v_mfma_f32_16x16x32_bf16 v[46:49], v[154:157], v[170:173], v[46:49]
	v_mfma_f32_16x16x32_bf16 v[22:25], v[146:149], v[166:169], v[22:25]
	v_mfma_f32_16x16x32_bf16 v[30:33], v[154:157], v[166:169], v[30:33]
	v_mfma_f32_16x16x32_bf16 v[10:13], v[146:149], v[162:165], v[10:13]
	v_mfma_f32_16x16x32_bf16 v[14:17], v[154:157], v[162:165], v[14:17]
	v_mfma_f32_16x16x32_bf16 v[54:57], v[150:153], v[190:193], v[54:57]
	v_mfma_f32_16x16x32_bf16 v[62:65], v[158:161], v[190:193], v[62:65]
	v_mfma_f32_16x16x32_bf16 v[38:41], v[150:153], v[186:189], v[38:41]
	v_mfma_f32_16x16x32_bf16 v[46:49], v[158:161], v[186:189], v[46:49]
	v_mfma_f32_16x16x32_bf16 v[22:25], v[150:153], v[182:185], v[22:25]
	v_mfma_f32_16x16x32_bf16 v[30:33], v[158:161], v[182:185], v[30:33]
	v_mfma_f32_16x16x32_bf16 v[10:13], v[150:153], v[178:181], v[10:13]
	v_mfma_f32_16x16x32_bf16 v[14:17], v[158:161], v[178:181], v[14:17]
	s_setprio 0
	s_setprio 1
	v_mfma_f32_16x16x32_bf16 v[58:61], v[130:133], v[174:177], v[58:61]
	v_mfma_f32_16x16x32_bf16 v[50:53], v[138:141], v[174:177], v[50:53]
	v_mfma_f32_16x16x32_bf16 v[42:45], v[130:133], v[170:173], v[42:45]
	v_mfma_f32_16x16x32_bf16 v[34:37], v[138:141], v[170:173], v[34:37]
	v_mfma_f32_16x16x32_bf16 v[26:29], v[130:133], v[166:169], v[26:29]
	v_mfma_f32_16x16x32_bf16 v[18:21], v[138:141], v[166:169], v[18:21]
	v_mfma_f32_16x16x32_bf16 v[6:9], v[130:133], v[162:165], v[6:9]
	v_mfma_f32_16x16x32_bf16 v[2:5], v[138:141], v[162:165], v[2:5]
	v_mfma_f32_16x16x32_bf16 v[58:61], v[134:137], v[190:193], v[58:61]
	v_mfma_f32_16x16x32_bf16 v[50:53], v[142:145], v[190:193], v[50:53]
	v_mfma_f32_16x16x32_bf16 v[42:45], v[134:137], v[186:189], v[42:45]
	v_mfma_f32_16x16x32_bf16 v[34:37], v[142:145], v[186:189], v[34:37]
	v_mfma_f32_16x16x32_bf16 v[26:29], v[134:137], v[182:185], v[26:29]
	v_mfma_f32_16x16x32_bf16 v[18:21], v[142:145], v[182:185], v[18:21]
	v_mfma_f32_16x16x32_bf16 v[6:9], v[134:137], v[178:181], v[6:9]
	v_mfma_f32_16x16x32_bf16 v[2:5], v[142:145], v[178:181], v[2:5]
	s_setprio 0
	s_branch .LBB0_175

.LBB0_559:
	ds_read_b128 v[146:149], v227
	ds_read_b128 v[150:153], v227 offset:1024
	ds_read_b128 v[154:157], v227 offset:2048
	ds_read_b128 v[158:161], v227 offset:3072
	ds_read_b128 v[130:133], v228
	ds_read_b128 v[134:137], v228 offset:1024
	ds_read_b128 v[138:141], v228 offset:2048
	ds_read_b128 v[142:145], v228 offset:3072
	v_lshl_add_u64 v[234:235], v[216:217], 0, s[58:59]
	s_add_i32 m0, s8, 0xc000
	s_waitcnt lgkmcnt(0)
	ds_read_b128 v[174:177], v229
	ds_read_b128 v[190:193], v229 offset:1024
	ds_read_b128 v[170:173], v229 offset:2048
	ds_read_b128 v[186:189], v229 offset:3072
	ds_read_b128 v[166:169], v229 offset:4096
	ds_read_b128 v[182:185], v229 offset:5120
	ds_read_b128 v[162:165], v229 offset:6144
	ds_read_b128 v[178:181], v229 offset:7168
	s_mov_b32 m0, s67
	s_nop 0
	global_load_lds_dwordx4 v196, s[100:101]
	s_add_i32 m0, s8, 0xc000
	s_nop 0
	global_load_lds_dwordx4 v[234:235], off
	v_lshl_add_u64 v[234:235], v[218:219], 0, s[58:59]
	s_add_i32 m0, s8, 0xe000
	s_nop 0
	global_load_lds_dwordx4 v[234:235], off
	s_waitcnt vmcnt(8)
	s_waitcnt lgkmcnt(0)
	s_barrier
	s_setprio 1
	s_waitcnt lgkmcnt(0)
	v_mfma_f32_16x16x32_bf16 v[126:129], v[146:149], v[174:177], v[126:129]
	v_mfma_f32_16x16x32_bf16 v[122:125], v[154:157], v[174:177], v[122:125]
	v_mfma_f32_16x16x32_bf16 v[110:113], v[146:149], v[170:173], v[110:113]
	v_mfma_f32_16x16x32_bf16 v[106:109], v[154:157], v[170:173], v[106:109]
	v_mfma_f32_16x16x32_bf16 v[94:97], v[146:149], v[166:169], v[94:97]
	v_mfma_f32_16x16x32_bf16 v[90:93], v[154:157], v[166:169], v[90:93]
	v_mfma_f32_16x16x32_bf16 v[78:81], v[146:149], v[162:165], v[78:81]
	v_mfma_f32_16x16x32_bf16 v[74:77], v[154:157], v[162:165], v[74:77]
	v_mfma_f32_16x16x32_bf16 v[126:129], v[150:153], v[190:193], v[126:129]
	v_mfma_f32_16x16x32_bf16 v[122:125], v[158:161], v[190:193], v[122:125]
	v_mfma_f32_16x16x32_bf16 v[110:113], v[150:153], v[186:189], v[110:113]
	v_mfma_f32_16x16x32_bf16 v[106:109], v[158:161], v[186:189], v[106:109]
	v_mfma_f32_16x16x32_bf16 v[94:97], v[150:153], v[182:185], v[94:97]
	v_mfma_f32_16x16x32_bf16 v[90:93], v[158:161], v[182:185], v[90:93]
	v_mfma_f32_16x16x32_bf16 v[78:81], v[150:153], v[178:181], v[78:81]
	v_mfma_f32_16x16x32_bf16 v[74:77], v[158:161], v[178:181], v[74:77]
	s_setprio 0
	s_setprio 1
	v_mfma_f32_16x16x32_bf16 v[118:121], v[130:133], v[174:177], v[118:121]
	v_mfma_f32_16x16x32_bf16 v[114:117], v[138:141], v[174:177], v[114:117]
	v_mfma_f32_16x16x32_bf16 v[102:105], v[130:133], v[170:173], v[102:105]
	v_mfma_f32_16x16x32_bf16 v[98:101], v[138:141], v[170:173], v[98:101]
	v_mfma_f32_16x16x32_bf16 v[86:89], v[130:133], v[166:169], v[86:89]
	v_mfma_f32_16x16x32_bf16 v[82:85], v[138:141], v[166:169], v[82:85]
	v_mfma_f32_16x16x32_bf16 v[70:73], v[130:133], v[162:165], v[70:73]
	v_mfma_f32_16x16x32_bf16 v[66:69], v[138:141], v[162:165], v[66:69]
	v_mfma_f32_16x16x32_bf16 v[118:121], v[134:137], v[190:193], v[118:121]
	v_mfma_f32_16x16x32_bf16 v[114:117], v[142:145], v[190:193], v[114:117]
	v_mfma_f32_16x16x32_bf16 v[102:105], v[134:137], v[186:189], v[102:105]
	v_mfma_f32_16x16x32_bf16 v[98:101], v[142:145], v[186:189], v[98:101]
	v_mfma_f32_16x16x32_bf16 v[86:89], v[134:137], v[182:185], v[86:89]
	v_mfma_f32_16x16x32_bf16 v[82:85], v[142:145], v[182:185], v[82:85]
	v_mfma_f32_16x16x32_bf16 v[70:73], v[134:137], v[178:181], v[70:73]
	v_mfma_f32_16x16x32_bf16 v[66:69], v[142:145], v[178:181], v[66:69]
	s_setprio 0
	s_barrier
	v_cmp_ne_u32_e64 s[42:43], 1, v233
	s_andn2_b64 vcc, exec, s[44:45]
	s_cbranch_vccnz .LBB0_561
	ds_read_b128 v[174:177], v229 offset:16384
	ds_read_b128 v[190:193], v229 offset:17408
	ds_read_b128 v[170:173], v229 offset:18432
	ds_read_b128 v[186:189], v229 offset:19456
	ds_read_b128 v[166:169], v229 offset:20480
	ds_read_b128 v[182:185], v229 offset:21504
	ds_read_b128 v[162:165], v229 offset:22528
	ds_read_b128 v[178:181], v229 offset:23552
.LBB0_561:
	s_add_u32 s60, s56, s58
	s_addc_u32 s61, s57, s59
	s_add_u32 s62, s60, 0x440000
	s_addc_u32 s63, s61, 0
	s_cmp_eq_u32 s58, 0x3fc0000
	s_cselect_b64 s[68:69], -1, 0
	s_and_b64 s[60:61], s[68:69], exec
	s_cselect_b32 s61, s37, s72
	s_cselect_b32 s60, s47, s53
	s_mov_b32 m0, s9
	s_cselect_b32 s63, s1, s63
	s_cselect_b32 s62, s24, s62
	v_lshl_add_u64 v[234:235], s[60:61], 0, v[194:195]
	s_add_u32 s74, s60, 0x4000
	global_load_lds_dwordx4 v[234:235], off
	v_lshl_add_u64 v[234:235], s[60:61], 0, v[196:197]
	s_mov_b32 m0, s10
	s_addc_u32 s75, s61, 0
	global_load_lds_dwordx4 v[234:235], off
	v_lshl_add_u64 v[234:235], s[74:75], 0, v[194:195]
	s_mov_b32 m0, s11
	s_and_b64 vcc, exec, s[42:43]
	global_load_lds_dwordx4 v[234:235], off
	v_lshl_add_u64 v[234:235], s[74:75], 0, v[196:197]
	s_mov_b32 m0, s12
	s_nop 0
	global_load_lds_dwordx4 v[234:235], off
	v_lshl_add_u64 v[234:235], s[62:63], 0, v[194:195]
	s_mov_b32 m0, s8
	s_nop 0
	global_load_lds_dwordx4 v[234:235], off
	s_mov_b64 s[98:99], s[62:63]
	s_waitcnt vmcnt(7)
	s_waitcnt lgkmcnt(0)
	s_barrier
	s_cbranch_vccnz .LBB0_563
	s_setprio 1
	s_waitcnt lgkmcnt(0)
	v_mfma_f32_16x16x32_bf16 v[62:65], v[146:149], v[174:177], v[62:65]
	v_mfma_f32_16x16x32_bf16 v[58:61], v[154:157], v[174:177], v[58:61]
	v_mfma_f32_16x16x32_bf16 v[46:49], v[146:149], v[170:173], v[46:49]
	v_mfma_f32_16x16x32_bf16 v[42:45], v[154:157], v[170:173], v[42:45]
	v_mfma_f32_16x16x32_bf16 v[30:33], v[146:149], v[166:169], v[30:33]
	v_mfma_f32_16x16x32_bf16 v[26:29], v[154:157], v[166:169], v[26:29]
	v_mfma_f32_16x16x32_bf16 v[14:17], v[146:149], v[162:165], v[14:17]
	v_mfma_f32_16x16x32_bf16 v[10:13], v[154:157], v[162:165], v[10:13]
	v_mfma_f32_16x16x32_bf16 v[62:65], v[150:153], v[190:193], v[62:65]
	v_mfma_f32_16x16x32_bf16 v[58:61], v[158:161], v[190:193], v[58:61]
	v_mfma_f32_16x16x32_bf16 v[46:49], v[150:153], v[186:189], v[46:49]
	v_mfma_f32_16x16x32_bf16 v[42:45], v[158:161], v[186:189], v[42:45]
	v_mfma_f32_16x16x32_bf16 v[30:33], v[150:153], v[182:185], v[30:33]
	v_mfma_f32_16x16x32_bf16 v[26:29], v[158:161], v[182:185], v[26:29]
	v_mfma_f32_16x16x32_bf16 v[14:17], v[150:153], v[178:181], v[14:17]
	v_mfma_f32_16x16x32_bf16 v[10:13], v[158:161], v[178:181], v[10:13]
	s_setprio 0
	s_setprio 1
	v_mfma_f32_16x16x32_bf16 v[54:57], v[130:133], v[174:177], v[54:57]
	v_mfma_f32_16x16x32_bf16 v[50:53], v[138:141], v[174:177], v[50:53]
	v_mfma_f32_16x16x32_bf16 v[38:41], v[130:133], v[170:173], v[38:41]
	v_mfma_f32_16x16x32_bf16 v[34:37], v[138:141], v[170:173], v[34:37]
	v_mfma_f32_16x16x32_bf16 v[22:25], v[130:133], v[166:169], v[22:25]
	v_mfma_f32_16x16x32_bf16 v[18:21], v[138:141], v[166:169], v[18:21]
	v_mfma_f32_16x16x32_bf16 v[6:9], v[130:133], v[162:165], v[6:9]
	v_mfma_f32_16x16x32_bf16 v[2:5], v[138:141], v[162:165], v[2:5]
	v_mfma_f32_16x16x32_bf16 v[54:57], v[134:137], v[190:193], v[54:57]
	v_mfma_f32_16x16x32_bf16 v[50:53], v[142:145], v[190:193], v[50:53]
	v_mfma_f32_16x16x32_bf16 v[38:41], v[134:137], v[186:189], v[38:41]
	v_mfma_f32_16x16x32_bf16 v[34:37], v[142:145], v[186:189], v[34:37]
	v_mfma_f32_16x16x32_bf16 v[22:25], v[134:137], v[182:185], v[22:25]
	v_mfma_f32_16x16x32_bf16 v[18:21], v[142:145], v[182:185], v[18:21]
	v_mfma_f32_16x16x32_bf16 v[6:9], v[134:137], v[178:181], v[6:9]
	v_mfma_f32_16x16x32_bf16 v[2:5], v[142:145], v[178:181], v[2:5]
	s_setprio 0
.LBB0_563:
	s_and_b64 vcc, s[40:41], s[68:69]
	v_cndmask_b32_e64 v131, v215, 0, vcc
	v_cndmask_b32_e32 v130, v214, v198, vcc
	v_lshl_add_u64 v[234:235], s[62:63], 0, v[130:131]
	s_barrier
	v_add_u32_e32 v130, 0x18000, v226
	v_add_u32_e32 v142, 0x1c000, v226
	ds_read_b128 v[146:149], v130
	ds_read_b128 v[150:153], v130 offset:1024
	ds_read_b128 v[154:157], v130 offset:2048
	ds_read_b128 v[158:161], v130 offset:3072
	ds_read_b128 v[130:133], v142
	ds_read_b128 v[134:137], v142 offset:1024
	ds_read_b128 v[138:141], v142 offset:2048
	ds_read_b128 v[142:145], v142 offset:3072
	s_mov_b32 m0, s14
	v_lshl_add_u64 v[236:237], v[234:235], 0, v[194:195]
	s_waitcnt lgkmcnt(0)
	ds_read_b128 v[174:177], v229 offset:32768
	ds_read_b128 v[190:193], v229 offset:33792
	ds_read_b128 v[170:173], v229 offset:34816
	ds_read_b128 v[186:189], v229 offset:35840
	ds_read_b128 v[166:169], v229 offset:36864
	ds_read_b128 v[182:185], v229 offset:37888
	ds_read_b128 v[162:165], v229 offset:38912
	ds_read_b128 v[178:181], v229 offset:39936
	s_mov_b32 m0, s13
	s_nop 0
	global_load_lds_dwordx4 v196, s[98:99]
	s_mov_b32 m0, s14
	s_nop 0
	global_load_lds_dwordx4 v[236:237], off
	v_lshl_add_u64 v[234:235], v[234:235], 0, v[196:197]
	s_mov_b32 m0, s15
	s_nop 0
	global_load_lds_dwordx4 v[234:235], off
	s_waitcnt vmcnt(8)
	s_waitcnt lgkmcnt(0)
	s_barrier
	s_setprio 1
	s_waitcnt lgkmcnt(0)
	v_mfma_f32_16x16x32_bf16 v[126:129], v[146:149], v[174:177], v[126:129]
	v_mfma_f32_16x16x32_bf16 v[122:125], v[154:157], v[174:177], v[122:125]
	v_mfma_f32_16x16x32_bf16 v[110:113], v[146:149], v[170:173], v[110:113]
	v_mfma_f32_16x16x32_bf16 v[106:109], v[154:157], v[170:173], v[106:109]
	v_mfma_f32_16x16x32_bf16 v[94:97], v[146:149], v[166:169], v[94:97]
	v_mfma_f32_16x16x32_bf16 v[90:93], v[154:157], v[166:169], v[90:93]
	v_mfma_f32_16x16x32_bf16 v[78:81], v[146:149], v[162:165], v[78:81]
	v_mfma_f32_16x16x32_bf16 v[74:77], v[154:157], v[162:165], v[74:77]
	v_mfma_f32_16x16x32_bf16 v[126:129], v[150:153], v[190:193], v[126:129]
	v_mfma_f32_16x16x32_bf16 v[122:125], v[158:161], v[190:193], v[122:125]
	v_mfma_f32_16x16x32_bf16 v[110:113], v[150:153], v[186:189], v[110:113]
	v_mfma_f32_16x16x32_bf16 v[106:109], v[158:161], v[186:189], v[106:109]
	v_mfma_f32_16x16x32_bf16 v[94:97], v[150:153], v[182:185], v[94:97]
	v_mfma_f32_16x16x32_bf16 v[90:93], v[158:161], v[182:185], v[90:93]
	v_mfma_f32_16x16x32_bf16 v[78:81], v[150:153], v[178:181], v[78:81]
	v_mfma_f32_16x16x32_bf16 v[74:77], v[158:161], v[178:181], v[74:77]
	s_setprio 0
	s_setprio 1
	v_mfma_f32_16x16x32_bf16 v[118:121], v[130:133], v[174:177], v[118:121]
	v_mfma_f32_16x16x32_bf16 v[114:117], v[138:141], v[174:177], v[114:117]
	v_mfma_f32_16x16x32_bf16 v[102:105], v[130:133], v[170:173], v[102:105]
	v_mfma_f32_16x16x32_bf16 v[98:101], v[138:141], v[170:173], v[98:101]
	v_mfma_f32_16x16x32_bf16 v[86:89], v[130:133], v[166:169], v[86:89]
	v_mfma_f32_16x16x32_bf16 v[82:85], v[138:141], v[166:169], v[82:85]
	v_mfma_f32_16x16x32_bf16 v[70:73], v[130:133], v[162:165], v[70:73]
	v_mfma_f32_16x16x32_bf16 v[66:69], v[138:141], v[162:165], v[66:69]
	v_mfma_f32_16x16x32_bf16 v[118:121], v[134:137], v[190:193], v[118:121]
	v_mfma_f32_16x16x32_bf16 v[114:117], v[142:145], v[190:193], v[114:117]
	v_mfma_f32_16x16x32_bf16 v[102:105], v[134:137], v[186:189], v[102:105]
	v_mfma_f32_16x16x32_bf16 v[98:101], v[142:145], v[186:189], v[98:101]
	v_mfma_f32_16x16x32_bf16 v[86:89], v[134:137], v[182:185], v[86:89]
	v_mfma_f32_16x16x32_bf16 v[82:85], v[142:145], v[182:185], v[82:85]
	v_mfma_f32_16x16x32_bf16 v[70:73], v[134:137], v[178:181], v[70:73]
	v_mfma_f32_16x16x32_bf16 v[66:69], v[142:145], v[178:181], v[66:69]
	s_setprio 0
	s_barrier
	s_and_b64 vcc, exec, s[42:43]
	s_cbranch_vccnz .LBB0_565
	ds_read_b128 v[174:177], v229 offset:49152
	ds_read_b128 v[190:193], v229 offset:50176
	ds_read_b128 v[170:173], v229 offset:51200
	ds_read_b128 v[186:189], v229 offset:52224
	ds_read_b128 v[166:169], v229 offset:53248
	ds_read_b128 v[182:185], v229 offset:54272
	ds_read_b128 v[162:165], v229 offset:55296
	ds_read_b128 v[178:181], v229 offset:56320
.LBB0_565:
	s_add_u32 s68, s60, 0x40000
	s_addc_u32 s69, s61, 0
	s_add_u32 s62, s62, 0x220000
	s_addc_u32 s63, s63, 0
	s_mov_b32 m0, s17
	v_lshl_add_u64 v[234:235], s[68:69], 0, v[194:195]
	s_add_u32 s60, s60, 0x44000
	global_load_lds_dwordx4 v[234:235], off
	v_lshl_add_u64 v[234:235], s[68:69], 0, v[196:197]
	s_mov_b32 m0, s54
	s_addc_u32 s61, s61, 0
	global_load_lds_dwordx4 v[234:235], off
	v_lshl_add_u64 v[234:235], s[60:61], 0, v[194:195]
	s_mov_b32 m0, s70
	s_and_b64 vcc, exec, s[42:43]
	global_load_lds_dwordx4 v[234:235], off
	v_lshl_add_u64 v[234:235], s[60:61], 0, v[196:197]
	s_mov_b32 m0, s71
	s_nop 0
	global_load_lds_dwordx4 v[234:235], off
	v_lshl_add_u64 v[234:235], s[62:63], 0, v[194:195]
	s_mov_b32 m0, s55
	s_nop 0
	global_load_lds_dwordx4 v[234:235], off
	s_mov_b64 s[100:101], s[62:63]
	s_waitcnt vmcnt(7)
	s_waitcnt lgkmcnt(0)
	s_barrier
	s_cbranch_vccnz .LBB0_558
	s_setprio 1
	s_waitcnt lgkmcnt(0)
	v_mfma_f32_16x16x32_bf16 v[62:65], v[146:149], v[174:177], v[62:65]
	v_mfma_f32_16x16x32_bf16 v[58:61], v[154:157], v[174:177], v[58:61]
	v_mfma_f32_16x16x32_bf16 v[46:49], v[146:149], v[170:173], v[46:49]
	v_mfma_f32_16x16x32_bf16 v[42:45], v[154:157], v[170:173], v[42:45]
	v_mfma_f32_16x16x32_bf16 v[30:33], v[146:149], v[166:169], v[30:33]
	v_mfma_f32_16x16x32_bf16 v[26:29], v[154:157], v[166:169], v[26:29]
	v_mfma_f32_16x16x32_bf16 v[14:17], v[146:149], v[162:165], v[14:17]
	v_mfma_f32_16x16x32_bf16 v[10:13], v[154:157], v[162:165], v[10:13]
	v_mfma_f32_16x16x32_bf16 v[62:65], v[150:153], v[190:193], v[62:65]
	v_mfma_f32_16x16x32_bf16 v[58:61], v[158:161], v[190:193], v[58:61]
	v_mfma_f32_16x16x32_bf16 v[46:49], v[150:153], v[186:189], v[46:49]
	v_mfma_f32_16x16x32_bf16 v[42:45], v[158:161], v[186:189], v[42:45]
	v_mfma_f32_16x16x32_bf16 v[30:33], v[150:153], v[182:185], v[30:33]
	v_mfma_f32_16x16x32_bf16 v[26:29], v[158:161], v[182:185], v[26:29]
	v_mfma_f32_16x16x32_bf16 v[14:17], v[150:153], v[178:181], v[14:17]
	v_mfma_f32_16x16x32_bf16 v[10:13], v[158:161], v[178:181], v[10:13]
	s_setprio 0
	s_setprio 1
	v_mfma_f32_16x16x32_bf16 v[54:57], v[130:133], v[174:177], v[54:57]
	v_mfma_f32_16x16x32_bf16 v[50:53], v[138:141], v[174:177], v[50:53]
	v_mfma_f32_16x16x32_bf16 v[38:41], v[130:133], v[170:173], v[38:41]
	v_mfma_f32_16x16x32_bf16 v[34:37], v[138:141], v[170:173], v[34:37]
	v_mfma_f32_16x16x32_bf16 v[22:25], v[130:133], v[166:169], v[22:25]
	v_mfma_f32_16x16x32_bf16 v[18:21], v[138:141], v[166:169], v[18:21]
	v_mfma_f32_16x16x32_bf16 v[6:9], v[130:133], v[162:165], v[6:9]
	v_mfma_f32_16x16x32_bf16 v[2:5], v[138:141], v[162:165], v[2:5]
	v_mfma_f32_16x16x32_bf16 v[54:57], v[134:137], v[190:193], v[54:57]
	v_mfma_f32_16x16x32_bf16 v[50:53], v[142:145], v[190:193], v[50:53]
	v_mfma_f32_16x16x32_bf16 v[38:41], v[134:137], v[186:189], v[38:41]
	v_mfma_f32_16x16x32_bf16 v[34:37], v[142:145], v[186:189], v[34:37]
	v_mfma_f32_16x16x32_bf16 v[22:25], v[134:137], v[182:185], v[22:25]
	v_mfma_f32_16x16x32_bf16 v[18:21], v[142:145], v[182:185], v[18:21]
	v_mfma_f32_16x16x32_bf16 v[6:9], v[134:137], v[178:181], v[6:9]
	v_mfma_f32_16x16x32_bf16 v[2:5], v[142:145], v[178:181], v[2:5]
	s_setprio 0
	s_branch .LBB0_558

.LBB0_761:
	ds_read_b128 v[130:133], v237
	ds_read_b128 v[134:137], v237 offset:1024
	ds_read_b128 v[138:141], v237 offset:2048
	ds_read_b128 v[142:145], v237 offset:3072
	ds_read_b128 v[146:149], v238
	ds_read_b128 v[150:153], v238 offset:1024
	ds_read_b128 v[154:157], v238 offset:2048
	ds_read_b128 v[158:161], v238 offset:3072
	s_add_u32 s48, s0, 0x21c000
	s_addc_u32 s49, s1, 0
	s_cmp_eq_u32 s67, 28
	s_cselect_b32 s42, s55, s62
	s_cselect_b32 s43, s29, s63
	s_cselect_b32 s52, s45, s48
	s_cselect_b32 s53, s31, s49
	s_add_u32 s50, s42, 0xe0000
	s_addc_u32 s51, s43, 0
	s_add_u32 s48, s52, 0x220000
	s_addc_u32 s49, s53, 0
	v_lshl_add_u64 v[208:209], s[0:1], 0, v[202:203]
	s_add_i32 m0, s9, 0xc000
	ds_read_b128 v[162:165], v239
	ds_read_b128 v[166:169], v239 offset:1024
	ds_read_b128 v[170:173], v239 offset:2048
	ds_read_b128 v[174:177], v239 offset:3072
	ds_read_b128 v[178:181], v239 offset:4096
	ds_read_b128 v[182:185], v239 offset:5120
	ds_read_b128 v[186:189], v239 offset:6144
	ds_read_b128 v[190:193], v239 offset:7168
	s_mov_b32 m0, s15
	s_nop 0
	global_load_lds_dwordx4 v196, s[100:101]
	s_add_i32 m0, s9, 0xc000
	s_nop 0
	global_load_lds_dwordx4 v[208:209], off
	v_lshl_add_u64 v[208:209], s[0:1], 0, v[200:201]
	s_add_i32 m0, s9, 0xe000
	s_nop 0
	global_load_lds_dwordx4 v[208:209], off
	s_waitcnt vmcnt(8)
	s_waitcnt lgkmcnt(0)
	s_barrier
	s_setprio 1
	s_waitcnt lgkmcnt(0)
	v_mfma_f32_16x16x32_bf16 v[126:129], v[130:133], v[162:165], v[126:129]
	v_mfma_f32_16x16x32_bf16 v[122:125], v[138:141], v[162:165], v[122:125]
	v_mfma_f32_16x16x32_bf16 v[118:121], v[130:133], v[170:173], v[118:121]
	v_mfma_f32_16x16x32_bf16 v[114:117], v[138:141], v[170:173], v[114:117]
	v_mfma_f32_16x16x32_bf16 v[110:113], v[130:133], v[178:181], v[110:113]
	v_mfma_f32_16x16x32_bf16 v[106:109], v[138:141], v[178:181], v[106:109]
	v_mfma_f32_16x16x32_bf16 v[102:105], v[130:133], v[186:189], v[102:105]
	v_mfma_f32_16x16x32_bf16 v[98:101], v[138:141], v[186:189], v[98:101]
	v_mfma_f32_16x16x32_bf16 v[126:129], v[134:137], v[166:169], v[126:129]
	v_mfma_f32_16x16x32_bf16 v[122:125], v[142:145], v[166:169], v[122:125]
	v_mfma_f32_16x16x32_bf16 v[118:121], v[134:137], v[174:177], v[118:121]
	v_mfma_f32_16x16x32_bf16 v[114:117], v[142:145], v[174:177], v[114:117]
	v_mfma_f32_16x16x32_bf16 v[110:113], v[134:137], v[182:185], v[110:113]
	v_mfma_f32_16x16x32_bf16 v[106:109], v[142:145], v[182:185], v[106:109]
	v_mfma_f32_16x16x32_bf16 v[102:105], v[134:137], v[190:193], v[102:105]
	v_mfma_f32_16x16x32_bf16 v[98:101], v[142:145], v[190:193], v[98:101]
	s_setprio 0
	s_setprio 1
	v_mfma_f32_16x16x32_bf16 v[62:65], v[146:149], v[162:165], v[62:65]
	s_add_u32 s60, s52, 0x4000
	s_addc_u32 s61, s53, 0
	v_mfma_f32_16x16x32_bf16 v[58:61], v[154:157], v[162:165], v[58:61]
	v_mfma_f32_16x16x32_bf16 v[54:57], v[146:149], v[170:173], v[54:57]
	v_mfma_f32_16x16x32_bf16 v[50:53], v[154:157], v[170:173], v[50:53]
	v_mfma_f32_16x16x32_bf16 v[46:49], v[146:149], v[178:181], v[46:49]
	v_mfma_f32_16x16x32_bf16 v[42:45], v[154:157], v[178:181], v[42:45]
	v_mfma_f32_16x16x32_bf16 v[38:41], v[146:149], v[186:189], v[38:41]
	v_mfma_f32_16x16x32_bf16 v[34:37], v[154:157], v[186:189], v[34:37]
	v_mfma_f32_16x16x32_bf16 v[62:65], v[150:153], v[166:169], v[62:65]
	v_mfma_f32_16x16x32_bf16 v[58:61], v[158:161], v[166:169], v[58:61]
	v_mfma_f32_16x16x32_bf16 v[54:57], v[150:153], v[174:177], v[54:57]
	v_mfma_f32_16x16x32_bf16 v[50:53], v[158:161], v[174:177], v[50:53]
	v_mfma_f32_16x16x32_bf16 v[46:49], v[150:153], v[182:185], v[46:49]
	v_mfma_f32_16x16x32_bf16 v[42:45], v[158:161], v[182:185], v[42:45]
	v_mfma_f32_16x16x32_bf16 v[38:41], v[150:153], v[190:193], v[38:41]
	v_mfma_f32_16x16x32_bf16 v[34:37], v[158:161], v[190:193], v[34:37]
	s_setprio 0
	s_barrier
	s_add_i32 s68, s16, s8
	v_lshl_add_u64 v[208:209], s[42:43], 0, v[194:195]
	s_mov_b32 m0, s68
	ds_read_b128 v[162:165], v239 offset:16384
	ds_read_b128 v[166:169], v239 offset:17408
	ds_read_b128 v[170:173], v239 offset:18432
	ds_read_b128 v[174:177], v239 offset:19456
	ds_read_b128 v[178:181], v239 offset:20480
	ds_read_b128 v[182:185], v239 offset:21504
	ds_read_b128 v[186:189], v239 offset:22528
	ds_read_b128 v[190:193], v239 offset:23552
	global_load_lds_dwordx4 v[208:209], off
	s_add_i32 m0, s68, 0x2000
	s_add_u32 s68, s42, 0x4000
	v_lshl_add_u64 v[208:209], s[42:43], 0, v[196:197]
	s_addc_u32 s69, s43, 0
	s_add_i32 s70, s17, s8
	global_load_lds_dwordx4 v[208:209], off
	v_lshl_add_u64 v[208:209], s[68:69], 0, v[194:195]
	s_mov_b32 m0, s70
	s_nop 0
	global_load_lds_dwordx4 v[208:209], off
	v_lshl_add_u64 v[208:209], s[68:69], 0, v[196:197]
	s_add_i32 m0, s70, 0x2000
	s_nop 0
	global_load_lds_dwordx4 v[208:209], off
	v_lshl_add_u64 v[208:209], s[52:53], 0, v[194:195]
	s_mov_b32 m0, s9
	s_nop 0
	global_load_lds_dwordx4 v[208:209], off
	s_mov_b64 s[98:99], s[52:53]
	s_waitcnt vmcnt(7)
	s_waitcnt lgkmcnt(0)
	s_barrier
	s_setprio 1
	s_waitcnt lgkmcnt(0)
	v_mfma_f32_16x16x32_bf16 v[94:97], v[130:133], v[162:165], v[94:97]
	v_mfma_f32_16x16x32_bf16 v[90:93], v[138:141], v[162:165], v[90:93]
	v_mfma_f32_16x16x32_bf16 v[86:89], v[130:133], v[170:173], v[86:89]
	v_mfma_f32_16x16x32_bf16 v[82:85], v[138:141], v[170:173], v[82:85]
	v_mfma_f32_16x16x32_bf16 v[78:81], v[130:133], v[178:181], v[78:81]
	v_mfma_f32_16x16x32_bf16 v[74:77], v[138:141], v[178:181], v[74:77]
	v_mfma_f32_16x16x32_bf16 v[70:73], v[130:133], v[186:189], v[70:73]
	v_mfma_f32_16x16x32_bf16 v[66:69], v[138:141], v[186:189], v[66:69]
	v_mfma_f32_16x16x32_bf16 v[94:97], v[134:137], v[166:169], v[94:97]
	v_mfma_f32_16x16x32_bf16 v[90:93], v[142:145], v[166:169], v[90:93]
	v_mfma_f32_16x16x32_bf16 v[86:89], v[134:137], v[174:177], v[86:89]
	v_mfma_f32_16x16x32_bf16 v[82:85], v[142:145], v[174:177], v[82:85]
	v_mfma_f32_16x16x32_bf16 v[78:81], v[134:137], v[182:185], v[78:81]
	v_mfma_f32_16x16x32_bf16 v[74:77], v[142:145], v[182:185], v[74:77]
	v_mfma_f32_16x16x32_bf16 v[70:73], v[134:137], v[190:193], v[70:73]
	v_mfma_f32_16x16x32_bf16 v[66:69], v[142:145], v[190:193], v[66:69]
	s_setprio 0
	s_setprio 1
	v_mfma_f32_16x16x32_bf16 v[30:33], v[146:149], v[162:165], v[30:33]
	v_mfma_f32_16x16x32_bf16 v[26:29], v[154:157], v[162:165], v[26:29]
	v_mfma_f32_16x16x32_bf16 v[22:25], v[146:149], v[170:173], v[22:25]
	v_mfma_f32_16x16x32_bf16 v[18:21], v[154:157], v[170:173], v[18:21]
	v_mfma_f32_16x16x32_bf16 v[14:17], v[146:149], v[178:181], v[14:17]
	v_mfma_f32_16x16x32_bf16 v[10:13], v[154:157], v[178:181], v[10:13]
	v_mfma_f32_16x16x32_bf16 v[6:9], v[146:149], v[186:189], v[6:9]
	v_mfma_f32_16x16x32_bf16 v[2:5], v[154:157], v[186:189], v[2:5]
	v_mfma_f32_16x16x32_bf16 v[30:33], v[150:153], v[166:169], v[30:33]
	v_mfma_f32_16x16x32_bf16 v[26:29], v[158:161], v[166:169], v[26:29]
	v_mfma_f32_16x16x32_bf16 v[22:25], v[150:153], v[174:177], v[22:25]
	v_mfma_f32_16x16x32_bf16 v[18:21], v[158:161], v[174:177], v[18:21]
	v_mfma_f32_16x16x32_bf16 v[14:17], v[150:153], v[182:185], v[14:17]
	v_mfma_f32_16x16x32_bf16 v[10:13], v[158:161], v[182:185], v[10:13]
	v_mfma_f32_16x16x32_bf16 v[6:9], v[150:153], v[190:193], v[6:9]
	v_mfma_f32_16x16x32_bf16 v[2:5], v[158:161], v[190:193], v[2:5]
	s_setprio 0
	s_barrier
	s_add_i32 s52, 0, 0x18000
	s_add_i32 s53, 0, 0x1c000
	v_add_u32_e32 v142, s52, v228
	v_add_u32_e32 v158, s53, v228
	ds_read_b128 v[130:133], v142
	ds_read_b128 v[134:137], v142 offset:1024
	ds_read_b128 v[138:141], v142 offset:2048
	ds_read_b128 v[142:145], v142 offset:3072
	ds_read_b128 v[146:149], v158
	ds_read_b128 v[150:153], v158 offset:1024
	ds_read_b128 v[154:157], v158 offset:2048
	ds_read_b128 v[158:161], v158 offset:3072
	s_mov_b32 m0, s11
	v_lshl_add_u64 v[208:209], s[60:61], 0, v[194:195]
	ds_read_b128 v[162:165], v239 offset:32768
	ds_read_b128 v[166:169], v239 offset:33792
	ds_read_b128 v[170:173], v239 offset:34816
	ds_read_b128 v[174:177], v239 offset:35840
	ds_read_b128 v[178:181], v239 offset:36864
	ds_read_b128 v[182:185], v239 offset:37888
	ds_read_b128 v[186:189], v239 offset:38912
	ds_read_b128 v[190:193], v239 offset:39936
	s_mov_b32 m0, s10
	s_nop 0
	global_load_lds_dwordx4 v196, s[98:99]
	s_mov_b32 m0, s11
	s_nop 0
	global_load_lds_dwordx4 v[208:209], off
	v_lshl_add_u64 v[208:209], s[60:61], 0, v[196:197]
	s_mov_b32 m0, s12
	s_nop 0
	global_load_lds_dwordx4 v[208:209], off
	s_waitcnt vmcnt(8)
	s_waitcnt lgkmcnt(0)
	s_barrier
	s_setprio 1
	s_waitcnt lgkmcnt(0)
	v_mfma_f32_16x16x32_bf16 v[126:129], v[130:133], v[162:165], v[126:129]
	v_mfma_f32_16x16x32_bf16 v[122:125], v[138:141], v[162:165], v[122:125]
	v_mfma_f32_16x16x32_bf16 v[118:121], v[130:133], v[170:173], v[118:121]
	v_mfma_f32_16x16x32_bf16 v[114:117], v[138:141], v[170:173], v[114:117]
	v_mfma_f32_16x16x32_bf16 v[110:113], v[130:133], v[178:181], v[110:113]
	v_mfma_f32_16x16x32_bf16 v[106:109], v[138:141], v[178:181], v[106:109]
	v_mfma_f32_16x16x32_bf16 v[102:105], v[130:133], v[186:189], v[102:105]
	v_mfma_f32_16x16x32_bf16 v[98:101], v[138:141], v[186:189], v[98:101]
	v_mfma_f32_16x16x32_bf16 v[126:129], v[134:137], v[166:169], v[126:129]
	v_mfma_f32_16x16x32_bf16 v[122:125], v[142:145], v[166:169], v[122:125]
	v_mfma_f32_16x16x32_bf16 v[118:121], v[134:137], v[174:177], v[118:121]
	v_mfma_f32_16x16x32_bf16 v[114:117], v[142:145], v[174:177], v[114:117]
	v_mfma_f32_16x16x32_bf16 v[110:113], v[134:137], v[182:185], v[110:113]
	v_mfma_f32_16x16x32_bf16 v[106:109], v[142:145], v[182:185], v[106:109]
	v_mfma_f32_16x16x32_bf16 v[102:105], v[134:137], v[190:193], v[102:105]
	v_mfma_f32_16x16x32_bf16 v[98:101], v[142:145], v[190:193], v[98:101]
	s_setprio 0
	s_setprio 1
	v_mfma_f32_16x16x32_bf16 v[62:65], v[146:149], v[162:165], v[62:65]
	v_mfma_f32_16x16x32_bf16 v[58:61], v[154:157], v[162:165], v[58:61]
	v_mfma_f32_16x16x32_bf16 v[54:57], v[146:149], v[170:173], v[54:57]
	v_mfma_f32_16x16x32_bf16 v[50:53], v[154:157], v[170:173], v[50:53]
	v_mfma_f32_16x16x32_bf16 v[46:49], v[146:149], v[178:181], v[46:49]
	v_mfma_f32_16x16x32_bf16 v[42:45], v[154:157], v[178:181], v[42:45]
	v_mfma_f32_16x16x32_bf16 v[38:41], v[146:149], v[186:189], v[38:41]
	v_mfma_f32_16x16x32_bf16 v[34:37], v[154:157], v[186:189], v[34:37]
	v_mfma_f32_16x16x32_bf16 v[62:65], v[150:153], v[166:169], v[62:65]
	v_mfma_f32_16x16x32_bf16 v[58:61], v[158:161], v[166:169], v[58:61]
	v_mfma_f32_16x16x32_bf16 v[54:57], v[150:153], v[174:177], v[54:57]
	v_mfma_f32_16x16x32_bf16 v[50:53], v[158:161], v[174:177], v[50:53]
	v_mfma_f32_16x16x32_bf16 v[46:49], v[150:153], v[182:185], v[46:49]
	v_mfma_f32_16x16x32_bf16 v[42:45], v[158:161], v[182:185], v[42:45]
	v_mfma_f32_16x16x32_bf16 v[38:41], v[150:153], v[190:193], v[38:41]
	v_mfma_f32_16x16x32_bf16 v[34:37], v[158:161], v[190:193], v[34:37]
	s_setprio 0
	s_barrier
	s_add_i32 s52, s52, s8
	v_lshl_add_u64 v[208:209], s[50:51], 0, v[194:195]
	s_mov_b32 m0, s52
	ds_read_b128 v[162:165], v239 offset:49152
	ds_read_b128 v[166:169], v239 offset:50176
	ds_read_b128 v[170:173], v239 offset:51200
	ds_read_b128 v[174:177], v239 offset:52224
	ds_read_b128 v[178:181], v239 offset:53248
	ds_read_b128 v[182:185], v239 offset:54272
	ds_read_b128 v[186:189], v239 offset:55296
	ds_read_b128 v[190:193], v239 offset:56320
	global_load_lds_dwordx4 v[208:209], off
	s_add_i32 m0, s52, 0x2000
	s_add_u32 s42, s42, 0xe4000
	v_lshl_add_u64 v[208:209], s[50:51], 0, v[196:197]
	s_addc_u32 s43, s43, 0
	s_add_i32 s50, s53, s8
	global_load_lds_dwordx4 v[208:209], off
	v_lshl_add_u64 v[208:209], s[42:43], 0, v[194:195]
	s_mov_b32 m0, s50
	s_nop 0
	global_load_lds_dwordx4 v[208:209], off
	v_lshl_add_u64 v[208:209], s[42:43], 0, v[196:197]
	s_add_i32 m0, s50, 0x2000
	s_nop 0
	global_load_lds_dwordx4 v[208:209], off
	v_lshl_add_u64 v[208:209], s[48:49], 0, v[194:195]
	s_mov_b32 m0, s14
	s_nop 0
	global_load_lds_dwordx4 v[208:209], off
	s_mov_b64 s[100:101], s[48:49]
	s_waitcnt vmcnt(7)
	s_waitcnt lgkmcnt(0)
	s_barrier
	s_setprio 1
	s_waitcnt lgkmcnt(0)
	v_mfma_f32_16x16x32_bf16 v[94:97], v[130:133], v[162:165], v[94:97]
	v_mfma_f32_16x16x32_bf16 v[90:93], v[138:141], v[162:165], v[90:93]
	v_mfma_f32_16x16x32_bf16 v[86:89], v[130:133], v[170:173], v[86:89]
	v_mfma_f32_16x16x32_bf16 v[82:85], v[138:141], v[170:173], v[82:85]
	v_mfma_f32_16x16x32_bf16 v[78:81], v[130:133], v[178:181], v[78:81]
	v_mfma_f32_16x16x32_bf16 v[74:77], v[138:141], v[178:181], v[74:77]
	v_mfma_f32_16x16x32_bf16 v[70:73], v[130:133], v[186:189], v[70:73]
	v_mfma_f32_16x16x32_bf16 v[66:69], v[138:141], v[186:189], v[66:69]
	v_mfma_f32_16x16x32_bf16 v[94:97], v[134:137], v[166:169], v[94:97]
	v_mfma_f32_16x16x32_bf16 v[90:93], v[142:145], v[166:169], v[90:93]
	v_mfma_f32_16x16x32_bf16 v[86:89], v[134:137], v[174:177], v[86:89]
	v_mfma_f32_16x16x32_bf16 v[82:85], v[142:145], v[174:177], v[82:85]
	v_mfma_f32_16x16x32_bf16 v[78:81], v[134:137], v[182:185], v[78:81]
	v_mfma_f32_16x16x32_bf16 v[74:77], v[142:145], v[182:185], v[74:77]
	v_mfma_f32_16x16x32_bf16 v[70:73], v[134:137], v[190:193], v[70:73]
	v_mfma_f32_16x16x32_bf16 v[66:69], v[142:145], v[190:193], v[66:69]
	s_setprio 0
	s_setprio 1
	v_mfma_f32_16x16x32_bf16 v[30:33], v[146:149], v[162:165], v[30:33]
	v_mfma_f32_16x16x32_bf16 v[26:29], v[154:157], v[162:165], v[26:29]
	v_mfma_f32_16x16x32_bf16 v[22:25], v[146:149], v[170:173], v[22:25]
	v_mfma_f32_16x16x32_bf16 v[18:21], v[154:157], v[170:173], v[18:21]
	v_mfma_f32_16x16x32_bf16 v[14:17], v[146:149], v[178:181], v[14:17]
	v_mfma_f32_16x16x32_bf16 v[10:13], v[154:157], v[178:181], v[10:13]
	v_mfma_f32_16x16x32_bf16 v[6:9], v[146:149], v[186:189], v[6:9]
	v_mfma_f32_16x16x32_bf16 v[2:5], v[154:157], v[186:189], v[2:5]
	v_mfma_f32_16x16x32_bf16 v[30:33], v[150:153], v[166:169], v[30:33]
	v_mfma_f32_16x16x32_bf16 v[26:29], v[158:161], v[166:169], v[26:29]
	v_mfma_f32_16x16x32_bf16 v[22:25], v[150:153], v[174:177], v[22:25]
	v_mfma_f32_16x16x32_bf16 v[18:21], v[158:161], v[174:177], v[18:21]
	v_mfma_f32_16x16x32_bf16 v[14:17], v[150:153], v[182:185], v[14:17]
	v_mfma_f32_16x16x32_bf16 v[10:13], v[158:161], v[182:185], v[10:13]
	v_mfma_f32_16x16x32_bf16 v[6:9], v[150:153], v[190:193], v[6:9]
	v_mfma_f32_16x16x32_bf16 v[2:5], v[158:161], v[190:193], v[2:5]
	s_setprio 0
	s_barrier
	s_add_i32 s67, s67, 2
	s_add_u32 s62, s62, 0x1c0000
	s_addc_u32 s63, s63, 0
	s_add_u32 s0, s0, 0x440000
	s_addc_u32 s1, s1, 0
	s_cmp_gt_u32 s67, 29
	s_cbranch_scc0 .LBB0_761
	s_and_b64 vcc, exec, s[26:27]
	s_cbranch_vccz .LBB0_764
	s_barrier

.LBB0_903:
	ds_read_b128 v[146:149], v225
	ds_read_b128 v[150:153], v225 offset:1024
	ds_read_b128 v[154:157], v225 offset:2048
	ds_read_b128 v[158:161], v225 offset:3072
	ds_read_b128 v[130:133], v227
	ds_read_b128 v[134:137], v227 offset:1024
	ds_read_b128 v[138:141], v227 offset:2048
	ds_read_b128 v[142:145], v227 offset:3072
	v_lshl_add_u64 v[234:235], v[210:211], 0, s[62:63]
	s_add_i32 m0, s8, 0xc000
	s_waitcnt lgkmcnt(0)
	ds_read_b128 v[174:177], v228
	ds_read_b128 v[190:193], v228 offset:1024
	ds_read_b128 v[170:173], v228 offset:2048
	ds_read_b128 v[186:189], v228 offset:3072
	ds_read_b128 v[166:169], v228 offset:4096
	ds_read_b128 v[182:185], v228 offset:5120
	ds_read_b128 v[162:165], v228 offset:6144
	ds_read_b128 v[178:181], v228 offset:7168
	s_mov_b32 m0, s31
	s_nop 0
	global_load_lds_dwordx4 v196, s[100:101]
	s_add_i32 m0, s8, 0xc000
	s_nop 0
	global_load_lds_dwordx4 v[234:235], off
	v_lshl_add_u64 v[234:235], v[212:213], 0, s[62:63]
	s_add_i32 m0, s8, 0xe000
	s_nop 0
	global_load_lds_dwordx4 v[234:235], off
	s_waitcnt vmcnt(8)
	s_waitcnt lgkmcnt(0)
	s_barrier
	s_setprio 1
	s_waitcnt lgkmcnt(0)
	v_mfma_f32_16x16x32_bf16 v[126:129], v[146:149], v[174:177], v[126:129]
	v_mfma_f32_16x16x32_bf16 v[122:125], v[154:157], v[174:177], v[122:125]
	v_mfma_f32_16x16x32_bf16 v[118:121], v[146:149], v[170:173], v[118:121]
	v_mfma_f32_16x16x32_bf16 v[114:117], v[154:157], v[170:173], v[114:117]
	v_mfma_f32_16x16x32_bf16 v[110:113], v[146:149], v[166:169], v[110:113]
	v_mfma_f32_16x16x32_bf16 v[106:109], v[154:157], v[166:169], v[106:109]
	v_mfma_f32_16x16x32_bf16 v[102:105], v[146:149], v[162:165], v[102:105]
	v_mfma_f32_16x16x32_bf16 v[98:101], v[154:157], v[162:165], v[98:101]
	v_mfma_f32_16x16x32_bf16 v[126:129], v[150:153], v[190:193], v[126:129]
	v_mfma_f32_16x16x32_bf16 v[122:125], v[158:161], v[190:193], v[122:125]
	v_mfma_f32_16x16x32_bf16 v[118:121], v[150:153], v[186:189], v[118:121]
	v_mfma_f32_16x16x32_bf16 v[114:117], v[158:161], v[186:189], v[114:117]
	v_mfma_f32_16x16x32_bf16 v[110:113], v[150:153], v[182:185], v[110:113]
	v_mfma_f32_16x16x32_bf16 v[106:109], v[158:161], v[182:185], v[106:109]
	v_mfma_f32_16x16x32_bf16 v[102:105], v[150:153], v[178:181], v[102:105]
	v_mfma_f32_16x16x32_bf16 v[98:101], v[158:161], v[178:181], v[98:101]
	s_setprio 0
	s_setprio 1
	v_mfma_f32_16x16x32_bf16 v[94:97], v[130:133], v[174:177], v[94:97]
	v_mfma_f32_16x16x32_bf16 v[90:93], v[138:141], v[174:177], v[90:93]
	v_mfma_f32_16x16x32_bf16 v[86:89], v[130:133], v[170:173], v[86:89]
	v_mfma_f32_16x16x32_bf16 v[82:85], v[138:141], v[170:173], v[82:85]
	v_mfma_f32_16x16x32_bf16 v[78:81], v[130:133], v[166:169], v[78:81]
	v_mfma_f32_16x16x32_bf16 v[74:77], v[138:141], v[166:169], v[74:77]
	v_mfma_f32_16x16x32_bf16 v[70:73], v[130:133], v[162:165], v[70:73]
	v_mfma_f32_16x16x32_bf16 v[66:69], v[138:141], v[162:165], v[66:69]
	v_mfma_f32_16x16x32_bf16 v[94:97], v[134:137], v[190:193], v[94:97]
	v_mfma_f32_16x16x32_bf16 v[90:93], v[142:145], v[190:193], v[90:93]
	v_mfma_f32_16x16x32_bf16 v[86:89], v[134:137], v[186:189], v[86:89]
	v_mfma_f32_16x16x32_bf16 v[82:85], v[142:145], v[186:189], v[82:85]
	v_mfma_f32_16x16x32_bf16 v[78:81], v[134:137], v[182:185], v[78:81]
	v_mfma_f32_16x16x32_bf16 v[74:77], v[142:145], v[182:185], v[74:77]
	v_mfma_f32_16x16x32_bf16 v[70:73], v[134:137], v[178:181], v[70:73]
	v_mfma_f32_16x16x32_bf16 v[66:69], v[142:145], v[178:181], v[66:69]
	s_setprio 0
	s_barrier
	v_cmp_ne_u32_e64 s[42:43], 1, v233
	s_andn2_b64 vcc, exec, s[44:45]
	s_cbranch_vccnz .LBB0_905
	ds_read_b128 v[174:177], v228 offset:16384
	ds_read_b128 v[190:193], v228 offset:17408
	ds_read_b128 v[170:173], v228 offset:18432
	ds_read_b128 v[186:189], v228 offset:19456
	ds_read_b128 v[166:169], v228 offset:20480
	ds_read_b128 v[182:185], v228 offset:21504
	ds_read_b128 v[162:165], v228 offset:22528
	ds_read_b128 v[178:181], v228 offset:23552
.LBB0_905:
	s_add_u32 s68, s0, s62
	s_addc_u32 s69, s1, s63
	s_add_u32 s70, s68, 0x440000
	s_addc_u32 s71, s69, 0
	s_cmp_eq_u32 s62, 0x3fc0000
	s_cselect_b64 s[72:73], -1, 0
	s_and_b64 s[68:69], s[72:73], exec
	s_cselect_b32 s69, s37, s77
	s_cselect_b32 s68, s75, s76
	s_mov_b32 m0, s9
	s_cselect_b32 s71, s35, s71
	s_cselect_b32 s70, s74, s70
	v_lshl_add_u64 v[234:235], s[68:69], 0, v[194:195]
	s_add_u32 s80, s68, 0x4000
	global_load_lds_dwordx4 v[234:235], off
	v_lshl_add_u64 v[234:235], s[68:69], 0, v[196:197]
	s_mov_b32 m0, s10
	s_addc_u32 s81, s69, 0
	global_load_lds_dwordx4 v[234:235], off
	v_lshl_add_u64 v[234:235], s[80:81], 0, v[194:195]
	s_mov_b32 m0, s11
	s_and_b64 vcc, exec, s[42:43]
	global_load_lds_dwordx4 v[234:235], off
	v_lshl_add_u64 v[234:235], s[80:81], 0, v[196:197]
	s_mov_b32 m0, s12
	s_nop 0
	global_load_lds_dwordx4 v[234:235], off
	v_lshl_add_u64 v[234:235], s[70:71], 0, v[194:195]
	s_mov_b32 m0, s8
	s_nop 0
	global_load_lds_dwordx4 v[234:235], off
	s_mov_b64 s[98:99], s[70:71]
	s_waitcnt vmcnt(7)
	s_waitcnt lgkmcnt(0)
	s_barrier
	s_cbranch_vccnz .LBB0_907
	s_setprio 1
	s_waitcnt lgkmcnt(0)
	v_mfma_f32_16x16x32_bf16 v[62:65], v[146:149], v[174:177], v[62:65]
	v_mfma_f32_16x16x32_bf16 v[58:61], v[154:157], v[174:177], v[58:61]
	v_mfma_f32_16x16x32_bf16 v[54:57], v[146:149], v[170:173], v[54:57]
	v_mfma_f32_16x16x32_bf16 v[50:53], v[154:157], v[170:173], v[50:53]
	v_mfma_f32_16x16x32_bf16 v[46:49], v[146:149], v[166:169], v[46:49]
	v_mfma_f32_16x16x32_bf16 v[42:45], v[154:157], v[166:169], v[42:45]
	v_mfma_f32_16x16x32_bf16 v[38:41], v[146:149], v[162:165], v[38:41]
	v_mfma_f32_16x16x32_bf16 v[34:37], v[154:157], v[162:165], v[34:37]
	v_mfma_f32_16x16x32_bf16 v[62:65], v[150:153], v[190:193], v[62:65]
	v_mfma_f32_16x16x32_bf16 v[58:61], v[158:161], v[190:193], v[58:61]
	v_mfma_f32_16x16x32_bf16 v[54:57], v[150:153], v[186:189], v[54:57]
	v_mfma_f32_16x16x32_bf16 v[50:53], v[158:161], v[186:189], v[50:53]
	v_mfma_f32_16x16x32_bf16 v[46:49], v[150:153], v[182:185], v[46:49]
	v_mfma_f32_16x16x32_bf16 v[42:45], v[158:161], v[182:185], v[42:45]
	v_mfma_f32_16x16x32_bf16 v[38:41], v[150:153], v[178:181], v[38:41]
	v_mfma_f32_16x16x32_bf16 v[34:37], v[158:161], v[178:181], v[34:37]
	s_setprio 0
	s_setprio 1
	v_mfma_f32_16x16x32_bf16 v[30:33], v[130:133], v[174:177], v[30:33]
	v_mfma_f32_16x16x32_bf16 v[26:29], v[138:141], v[174:177], v[26:29]
	v_mfma_f32_16x16x32_bf16 v[22:25], v[130:133], v[170:173], v[22:25]
	v_mfma_f32_16x16x32_bf16 v[18:21], v[138:141], v[170:173], v[18:21]
	v_mfma_f32_16x16x32_bf16 v[14:17], v[130:133], v[166:169], v[14:17]
	v_mfma_f32_16x16x32_bf16 v[10:13], v[138:141], v[166:169], v[10:13]
	v_mfma_f32_16x16x32_bf16 v[6:9], v[130:133], v[162:165], v[6:9]
	v_mfma_f32_16x16x32_bf16 v[2:5], v[138:141], v[162:165], v[2:5]
	v_mfma_f32_16x16x32_bf16 v[30:33], v[134:137], v[190:193], v[30:33]
	v_mfma_f32_16x16x32_bf16 v[26:29], v[142:145], v[190:193], v[26:29]
	v_mfma_f32_16x16x32_bf16 v[22:25], v[134:137], v[186:189], v[22:25]
	v_mfma_f32_16x16x32_bf16 v[18:21], v[142:145], v[186:189], v[18:21]
	v_mfma_f32_16x16x32_bf16 v[14:17], v[134:137], v[182:185], v[14:17]
	v_mfma_f32_16x16x32_bf16 v[10:13], v[142:145], v[182:185], v[10:13]
	v_mfma_f32_16x16x32_bf16 v[6:9], v[134:137], v[178:181], v[6:9]
	v_mfma_f32_16x16x32_bf16 v[2:5], v[142:145], v[178:181], v[2:5]
	s_setprio 0
.LBB0_907:
	s_and_b64 vcc, s[40:41], s[72:73]
	v_cndmask_b32_e64 v131, v209, 0, vcc
	v_cndmask_b32_e32 v130, v208, v198, vcc
	v_lshl_add_u64 v[234:235], s[70:71], 0, v[130:131]
	s_barrier
	v_add_u32_e32 v130, 0x18000, v224
	v_add_u32_e32 v142, 0x1c000, v224
	ds_read_b128 v[146:149], v130
	ds_read_b128 v[150:153], v130 offset:1024
	ds_read_b128 v[154:157], v130 offset:2048
	ds_read_b128 v[158:161], v130 offset:3072
	ds_read_b128 v[130:133], v142
	ds_read_b128 v[134:137], v142 offset:1024
	ds_read_b128 v[138:141], v142 offset:2048
	ds_read_b128 v[142:145], v142 offset:3072
	s_mov_b32 m0, s14
	v_lshl_add_u64 v[236:237], v[234:235], 0, v[194:195]
	s_waitcnt lgkmcnt(0)
	ds_read_b128 v[174:177], v228 offset:32768
	ds_read_b128 v[190:193], v228 offset:33792
	ds_read_b128 v[170:173], v228 offset:34816
	ds_read_b128 v[186:189], v228 offset:35840
	ds_read_b128 v[166:169], v228 offset:36864
	ds_read_b128 v[182:185], v228 offset:37888
	ds_read_b128 v[162:165], v228 offset:38912
	ds_read_b128 v[178:181], v228 offset:39936
	s_mov_b32 m0, s13
	s_nop 0
	global_load_lds_dwordx4 v196, s[98:99]
	s_mov_b32 m0, s14
	s_nop 0
	global_load_lds_dwordx4 v[236:237], off
	v_lshl_add_u64 v[234:235], v[234:235], 0, v[196:197]
	s_mov_b32 m0, s15
	s_nop 0
	global_load_lds_dwordx4 v[234:235], off
	s_waitcnt vmcnt(8)
	s_waitcnt lgkmcnt(0)
	s_barrier
	s_setprio 1
	s_waitcnt lgkmcnt(0)
	v_mfma_f32_16x16x32_bf16 v[126:129], v[146:149], v[174:177], v[126:129]
	v_mfma_f32_16x16x32_bf16 v[122:125], v[154:157], v[174:177], v[122:125]
	v_mfma_f32_16x16x32_bf16 v[118:121], v[146:149], v[170:173], v[118:121]
	v_mfma_f32_16x16x32_bf16 v[114:117], v[154:157], v[170:173], v[114:117]
	v_mfma_f32_16x16x32_bf16 v[110:113], v[146:149], v[166:169], v[110:113]
	v_mfma_f32_16x16x32_bf16 v[106:109], v[154:157], v[166:169], v[106:109]
	v_mfma_f32_16x16x32_bf16 v[102:105], v[146:149], v[162:165], v[102:105]
	v_mfma_f32_16x16x32_bf16 v[98:101], v[154:157], v[162:165], v[98:101]
	v_mfma_f32_16x16x32_bf16 v[126:129], v[150:153], v[190:193], v[126:129]
	v_mfma_f32_16x16x32_bf16 v[122:125], v[158:161], v[190:193], v[122:125]
	v_mfma_f32_16x16x32_bf16 v[118:121], v[150:153], v[186:189], v[118:121]
	v_mfma_f32_16x16x32_bf16 v[114:117], v[158:161], v[186:189], v[114:117]
	v_mfma_f32_16x16x32_bf16 v[110:113], v[150:153], v[182:185], v[110:113]
	v_mfma_f32_16x16x32_bf16 v[106:109], v[158:161], v[182:185], v[106:109]
	v_mfma_f32_16x16x32_bf16 v[102:105], v[150:153], v[178:181], v[102:105]
	v_mfma_f32_16x16x32_bf16 v[98:101], v[158:161], v[178:181], v[98:101]
	s_setprio 0
	s_setprio 1
	v_mfma_f32_16x16x32_bf16 v[94:97], v[130:133], v[174:177], v[94:97]
	v_mfma_f32_16x16x32_bf16 v[90:93], v[138:141], v[174:177], v[90:93]
	v_mfma_f32_16x16x32_bf16 v[86:89], v[130:133], v[170:173], v[86:89]
	v_mfma_f32_16x16x32_bf16 v[82:85], v[138:141], v[170:173], v[82:85]
	v_mfma_f32_16x16x32_bf16 v[78:81], v[130:133], v[166:169], v[78:81]
	v_mfma_f32_16x16x32_bf16 v[74:77], v[138:141], v[166:169], v[74:77]
	v_mfma_f32_16x16x32_bf16 v[70:73], v[130:133], v[162:165], v[70:73]
	v_mfma_f32_16x16x32_bf16 v[66:69], v[138:141], v[162:165], v[66:69]
	v_mfma_f32_16x16x32_bf16 v[94:97], v[134:137], v[190:193], v[94:97]
	v_mfma_f32_16x16x32_bf16 v[90:93], v[142:145], v[190:193], v[90:93]
	v_mfma_f32_16x16x32_bf16 v[86:89], v[134:137], v[186:189], v[86:89]
	v_mfma_f32_16x16x32_bf16 v[82:85], v[142:145], v[186:189], v[82:85]
	v_mfma_f32_16x16x32_bf16 v[78:81], v[134:137], v[182:185], v[78:81]
	v_mfma_f32_16x16x32_bf16 v[74:77], v[142:145], v[182:185], v[74:77]
	v_mfma_f32_16x16x32_bf16 v[70:73], v[134:137], v[178:181], v[70:73]
	v_mfma_f32_16x16x32_bf16 v[66:69], v[142:145], v[178:181], v[66:69]
	s_setprio 0
	s_barrier
	s_and_b64 vcc, exec, s[42:43]
	s_cbranch_vccnz .LBB0_909
	ds_read_b128 v[174:177], v228 offset:49152
	ds_read_b128 v[190:193], v228 offset:50176
	ds_read_b128 v[170:173], v228 offset:51200
	ds_read_b128 v[186:189], v228 offset:52224
	ds_read_b128 v[166:169], v228 offset:53248
	ds_read_b128 v[182:185], v228 offset:54272
	ds_read_b128 v[162:165], v228 offset:55296
	ds_read_b128 v[178:181], v228 offset:56320
.LBB0_909:
	s_add_u32 s72, s68, 0xe0000
	s_addc_u32 s73, s69, 0
	s_add_u32 s70, s70, 0x220000
	s_addc_u32 s71, s71, 0
	s_mov_b32 m0, s16
	v_lshl_add_u64 v[234:235], s[72:73], 0, v[194:195]
	s_add_u32 s68, s68, 0xe4000
	global_load_lds_dwordx4 v[234:235], off
	v_lshl_add_u64 v[234:235], s[72:73], 0, v[196:197]
	s_mov_b32 m0, s17
	s_addc_u32 s69, s69, 0
	global_load_lds_dwordx4 v[234:235], off
	v_lshl_add_u64 v[234:235], s[68:69], 0, v[194:195]
	s_mov_b32 m0, s54
	s_and_b64 vcc, exec, s[42:43]
	global_load_lds_dwordx4 v[234:235], off
	v_lshl_add_u64 v[234:235], s[68:69], 0, v[196:197]
	s_mov_b32 m0, s55
	s_nop 0
	global_load_lds_dwordx4 v[234:235], off
	v_lshl_add_u64 v[234:235], s[70:71], 0, v[194:195]
	s_mov_b32 m0, s23
	s_nop 0
	global_load_lds_dwordx4 v[234:235], off
	s_mov_b64 s[100:101], s[70:71]
	s_waitcnt vmcnt(7)
	s_waitcnt lgkmcnt(0)
	s_barrier
	s_cbranch_vccnz .LBB0_902
	s_setprio 1
	s_waitcnt lgkmcnt(0)
	v_mfma_f32_16x16x32_bf16 v[62:65], v[146:149], v[174:177], v[62:65]
	v_mfma_f32_16x16x32_bf16 v[58:61], v[154:157], v[174:177], v[58:61]
	v_mfma_f32_16x16x32_bf16 v[54:57], v[146:149], v[170:173], v[54:57]
	v_mfma_f32_16x16x32_bf16 v[50:53], v[154:157], v[170:173], v[50:53]
	v_mfma_f32_16x16x32_bf16 v[46:49], v[146:149], v[166:169], v[46:49]
	v_mfma_f32_16x16x32_bf16 v[42:45], v[154:157], v[166:169], v[42:45]
	v_mfma_f32_16x16x32_bf16 v[38:41], v[146:149], v[162:165], v[38:41]
	v_mfma_f32_16x16x32_bf16 v[34:37], v[154:157], v[162:165], v[34:37]
	v_mfma_f32_16x16x32_bf16 v[62:65], v[150:153], v[190:193], v[62:65]
	v_mfma_f32_16x16x32_bf16 v[58:61], v[158:161], v[190:193], v[58:61]
	v_mfma_f32_16x16x32_bf16 v[54:57], v[150:153], v[186:189], v[54:57]
	v_mfma_f32_16x16x32_bf16 v[50:53], v[158:161], v[186:189], v[50:53]
	v_mfma_f32_16x16x32_bf16 v[46:49], v[150:153], v[182:185], v[46:49]
	v_mfma_f32_16x16x32_bf16 v[42:45], v[158:161], v[182:185], v[42:45]
	v_mfma_f32_16x16x32_bf16 v[38:41], v[150:153], v[178:181], v[38:41]
	v_mfma_f32_16x16x32_bf16 v[34:37], v[158:161], v[178:181], v[34:37]
	s_setprio 0
	s_setprio 1
	v_mfma_f32_16x16x32_bf16 v[30:33], v[130:133], v[174:177], v[30:33]
	v_mfma_f32_16x16x32_bf16 v[26:29], v[138:141], v[174:177], v[26:29]
	v_mfma_f32_16x16x32_bf16 v[22:25], v[130:133], v[170:173], v[22:25]
	v_mfma_f32_16x16x32_bf16 v[18:21], v[138:141], v[170:173], v[18:21]
	v_mfma_f32_16x16x32_bf16 v[14:17], v[130:133], v[166:169], v[14:17]
	v_mfma_f32_16x16x32_bf16 v[10:13], v[138:141], v[166:169], v[10:13]
	v_mfma_f32_16x16x32_bf16 v[6:9], v[130:133], v[162:165], v[6:9]
	v_mfma_f32_16x16x32_bf16 v[2:5], v[138:141], v[162:165], v[2:5]
	v_mfma_f32_16x16x32_bf16 v[30:33], v[134:137], v[190:193], v[30:33]
	v_mfma_f32_16x16x32_bf16 v[26:29], v[142:145], v[190:193], v[26:29]
	v_mfma_f32_16x16x32_bf16 v[22:25], v[134:137], v[186:189], v[22:25]
	v_mfma_f32_16x16x32_bf16 v[18:21], v[142:145], v[186:189], v[18:21]
	v_mfma_f32_16x16x32_bf16 v[14:17], v[134:137], v[182:185], v[14:17]
	v_mfma_f32_16x16x32_bf16 v[10:13], v[142:145], v[182:185], v[10:13]
	v_mfma_f32_16x16x32_bf16 v[6:9], v[134:137], v[178:181], v[6:9]
	v_mfma_f32_16x16x32_bf16 v[2:5], v[142:145], v[178:181], v[2:5]
	s_setprio 0
	s_branch .LBB0_902

.LBB0_1289:
	v_add_u32_e32 v142, 0x14000, v229
	ds_read_b128 v[146:149], v230
	ds_read_b128 v[150:153], v230 offset:1024
	ds_read_b128 v[154:157], v230 offset:2048
	ds_read_b128 v[158:161], v230 offset:3072
	ds_read_b128 v[130:133], v142
	ds_read_b128 v[134:137], v142 offset:1024
	ds_read_b128 v[138:141], v142 offset:2048
	ds_read_b128 v[142:145], v142 offset:3072
	v_lshl_add_u64 v[234:235], v[222:223], 0, s[48:49]
	s_add_i32 m0, s8, 0xc000
	s_waitcnt lgkmcnt(0)
	ds_read_b128 v[174:177], v231
	ds_read_b128 v[190:193], v231 offset:1024
	ds_read_b128 v[170:173], v231 offset:2048
	ds_read_b128 v[186:189], v231 offset:3072
	ds_read_b128 v[166:169], v231 offset:4096
	ds_read_b128 v[182:185], v231 offset:5120
	ds_read_b128 v[162:165], v231 offset:6144
	ds_read_b128 v[178:181], v231 offset:7168
	s_mov_b32 m0, s54
	s_nop 0
	global_load_lds_dwordx4 v196, s[100:101]
	s_add_i32 m0, s8, 0xc000
	s_nop 0
	global_load_lds_dwordx4 v[234:235], off
	v_lshl_add_u64 v[234:235], v[224:225], 0, s[48:49]
	s_add_i32 m0, s8, 0xe000
	s_nop 0
	global_load_lds_dwordx4 v[234:235], off
	s_waitcnt vmcnt(8)
	s_waitcnt lgkmcnt(0)
	s_barrier
	s_setprio 1
	s_waitcnt lgkmcnt(0)
	v_mfma_f32_16x16x32_bf16 v[126:129], v[146:149], v[174:177], v[126:129]
	v_mfma_f32_16x16x32_bf16 v[122:125], v[154:157], v[174:177], v[122:125]
	v_mfma_f32_16x16x32_bf16 v[118:121], v[146:149], v[170:173], v[118:121]
	v_mfma_f32_16x16x32_bf16 v[110:113], v[154:157], v[170:173], v[110:113]
	v_mfma_f32_16x16x32_bf16 v[102:105], v[146:149], v[166:169], v[102:105]
	v_mfma_f32_16x16x32_bf16 v[94:97], v[154:157], v[166:169], v[94:97]
	v_mfma_f32_16x16x32_bf16 v[86:89], v[146:149], v[162:165], v[86:89]
	v_mfma_f32_16x16x32_bf16 v[78:81], v[154:157], v[162:165], v[78:81]
	v_mfma_f32_16x16x32_bf16 v[126:129], v[150:153], v[190:193], v[126:129]
	v_mfma_f32_16x16x32_bf16 v[122:125], v[158:161], v[190:193], v[122:125]
	v_mfma_f32_16x16x32_bf16 v[118:121], v[150:153], v[186:189], v[118:121]
	v_mfma_f32_16x16x32_bf16 v[110:113], v[158:161], v[186:189], v[110:113]
	v_mfma_f32_16x16x32_bf16 v[102:105], v[150:153], v[182:185], v[102:105]
	v_mfma_f32_16x16x32_bf16 v[94:97], v[158:161], v[182:185], v[94:97]
	v_mfma_f32_16x16x32_bf16 v[86:89], v[150:153], v[178:181], v[86:89]
	v_mfma_f32_16x16x32_bf16 v[78:81], v[158:161], v[178:181], v[78:81]
	s_setprio 0
	s_setprio 1
	v_mfma_f32_16x16x32_bf16 v[114:117], v[130:133], v[174:177], v[114:117]
	v_mfma_f32_16x16x32_bf16 v[106:109], v[138:141], v[174:177], v[106:109]
	v_mfma_f32_16x16x32_bf16 v[98:101], v[130:133], v[170:173], v[98:101]
	v_mfma_f32_16x16x32_bf16 v[90:93], v[138:141], v[170:173], v[90:93]
	v_mfma_f32_16x16x32_bf16 v[82:85], v[130:133], v[166:169], v[82:85]
	v_mfma_f32_16x16x32_bf16 v[74:77], v[138:141], v[166:169], v[74:77]
	v_mfma_f32_16x16x32_bf16 v[70:73], v[130:133], v[162:165], v[70:73]
	v_mfma_f32_16x16x32_bf16 v[66:69], v[138:141], v[162:165], v[66:69]
	v_mfma_f32_16x16x32_bf16 v[114:117], v[134:137], v[190:193], v[114:117]
	v_mfma_f32_16x16x32_bf16 v[106:109], v[142:145], v[190:193], v[106:109]
	v_mfma_f32_16x16x32_bf16 v[98:101], v[134:137], v[186:189], v[98:101]
	v_mfma_f32_16x16x32_bf16 v[90:93], v[142:145], v[186:189], v[90:93]
	v_mfma_f32_16x16x32_bf16 v[82:85], v[134:137], v[182:185], v[82:85]
	v_mfma_f32_16x16x32_bf16 v[74:77], v[142:145], v[182:185], v[74:77]
	v_mfma_f32_16x16x32_bf16 v[70:73], v[134:137], v[178:181], v[70:73]
	v_mfma_f32_16x16x32_bf16 v[66:69], v[142:145], v[178:181], v[66:69]
	s_setprio 0
	s_barrier
	v_cndmask_b32_e64 v233, 0, 1, s[40:41]
	v_cmp_ne_u32_e64 s[42:43], 1, v233
	s_andn2_b64 vcc, exec, s[40:41]
	s_cbranch_vccnz .LBB0_1291
	ds_read_b128 v[174:177], v231 offset:16384
	ds_read_b128 v[190:193], v231 offset:17408
	ds_read_b128 v[170:173], v231 offset:18432
	ds_read_b128 v[186:189], v231 offset:19456
	ds_read_b128 v[166:169], v231 offset:20480
	ds_read_b128 v[182:185], v231 offset:21504
	ds_read_b128 v[162:165], v231 offset:22528
	ds_read_b128 v[178:181], v231 offset:23552
.LBB0_1291:
	s_add_u32 s52, s36, s48
	s_addc_u32 s53, s37, s49
	s_add_u32 s56, s52, 0x440000
	s_addc_u32 s57, s53, 0
	s_cmp_eq_u32 s48, 0x3fc0000
	s_cselect_b64 s[58:59], -1, 0
	s_and_b64 s[52:53], s[58:59], exec
	s_cselect_b32 s53, s31, s63
	s_cselect_b32 s52, s61, s62
	s_mov_b32 m0, s9
	s_cselect_b32 s57, s19, s57
	s_cselect_b32 s56, s29, s56
	v_lshl_add_u64 v[234:235], s[52:53], 0, v[194:195]
	s_add_u32 s68, s52, 0x4000
	global_load_lds_dwordx4 v[234:235], off
	v_lshl_add_u64 v[234:235], s[52:53], 0, v[196:197]
	s_mov_b32 m0, s10
	s_addc_u32 s69, s53, 0
	global_load_lds_dwordx4 v[234:235], off
	v_lshl_add_u64 v[234:235], s[68:69], 0, v[194:195]
	s_mov_b32 m0, s11
	s_and_b64 vcc, exec, s[42:43]
	global_load_lds_dwordx4 v[234:235], off
	v_lshl_add_u64 v[234:235], s[68:69], 0, v[196:197]
	s_mov_b32 m0, s12
	s_nop 0
	global_load_lds_dwordx4 v[234:235], off
	v_lshl_add_u64 v[234:235], s[56:57], 0, v[194:195]
	s_mov_b32 m0, s8
	s_nop 0
	global_load_lds_dwordx4 v[234:235], off
	s_mov_b64 s[98:99], s[56:57]
	s_waitcnt vmcnt(7)
	s_waitcnt lgkmcnt(0)
	s_barrier
	s_cbranch_vccnz .LBB0_1293
	s_setprio 1
	s_waitcnt lgkmcnt(0)
	v_mfma_f32_16x16x32_bf16 v[62:65], v[146:149], v[174:177], v[62:65]
	v_mfma_f32_16x16x32_bf16 v[58:61], v[154:157], v[174:177], v[58:61]
	v_mfma_f32_16x16x32_bf16 v[46:49], v[146:149], v[170:173], v[46:49]
	v_mfma_f32_16x16x32_bf16 v[42:45], v[154:157], v[170:173], v[42:45]
	v_mfma_f32_16x16x32_bf16 v[30:33], v[146:149], v[166:169], v[30:33]
	v_mfma_f32_16x16x32_bf16 v[26:29], v[154:157], v[166:169], v[26:29]
	v_mfma_f32_16x16x32_bf16 v[14:17], v[146:149], v[162:165], v[14:17]
	v_mfma_f32_16x16x32_bf16 v[10:13], v[154:157], v[162:165], v[10:13]
	v_mfma_f32_16x16x32_bf16 v[62:65], v[150:153], v[190:193], v[62:65]
	v_mfma_f32_16x16x32_bf16 v[58:61], v[158:161], v[190:193], v[58:61]
	v_mfma_f32_16x16x32_bf16 v[46:49], v[150:153], v[186:189], v[46:49]
	v_mfma_f32_16x16x32_bf16 v[42:45], v[158:161], v[186:189], v[42:45]
	v_mfma_f32_16x16x32_bf16 v[30:33], v[150:153], v[182:185], v[30:33]
	v_mfma_f32_16x16x32_bf16 v[26:29], v[158:161], v[182:185], v[26:29]
	v_mfma_f32_16x16x32_bf16 v[14:17], v[150:153], v[178:181], v[14:17]
	v_mfma_f32_16x16x32_bf16 v[10:13], v[158:161], v[178:181], v[10:13]
	s_setprio 0
	s_setprio 1
	v_mfma_f32_16x16x32_bf16 v[54:57], v[130:133], v[174:177], v[54:57]
	v_mfma_f32_16x16x32_bf16 v[50:53], v[138:141], v[174:177], v[50:53]
	v_mfma_f32_16x16x32_bf16 v[38:41], v[130:133], v[170:173], v[38:41]
	v_mfma_f32_16x16x32_bf16 v[34:37], v[138:141], v[170:173], v[34:37]
	v_mfma_f32_16x16x32_bf16 v[22:25], v[130:133], v[166:169], v[22:25]
	v_mfma_f32_16x16x32_bf16 v[18:21], v[138:141], v[166:169], v[18:21]
	v_mfma_f32_16x16x32_bf16 v[6:9], v[130:133], v[162:165], v[6:9]
	v_mfma_f32_16x16x32_bf16 v[2:5], v[138:141], v[162:165], v[2:5]
	v_mfma_f32_16x16x32_bf16 v[54:57], v[134:137], v[190:193], v[54:57]
	v_mfma_f32_16x16x32_bf16 v[50:53], v[142:145], v[190:193], v[50:53]
	v_mfma_f32_16x16x32_bf16 v[38:41], v[134:137], v[186:189], v[38:41]
	v_mfma_f32_16x16x32_bf16 v[34:37], v[142:145], v[186:189], v[34:37]
	v_mfma_f32_16x16x32_bf16 v[22:25], v[134:137], v[182:185], v[22:25]
	v_mfma_f32_16x16x32_bf16 v[18:21], v[142:145], v[182:185], v[18:21]
	v_mfma_f32_16x16x32_bf16 v[6:9], v[134:137], v[178:181], v[6:9]
	v_mfma_f32_16x16x32_bf16 v[2:5], v[142:145], v[178:181], v[2:5]
	s_setprio 0
.LBB0_1293:
	s_and_b64 vcc, s[34:35], s[58:59]
	v_cndmask_b32_e64 v131, v221, 0, vcc
	v_cndmask_b32_e32 v130, v220, v198, vcc
	v_lshl_add_u64 v[234:235], s[56:57], 0, v[130:131]
	s_barrier
	v_add_u32_e32 v130, 0x18000, v229
	v_add_u32_e32 v142, 0x1c000, v229
	ds_read_b128 v[146:149], v130
	ds_read_b128 v[150:153], v130 offset:1024
	ds_read_b128 v[154:157], v130 offset:2048
	ds_read_b128 v[158:161], v130 offset:3072
	ds_read_b128 v[130:133], v142
	ds_read_b128 v[134:137], v142 offset:1024
	ds_read_b128 v[138:141], v142 offset:2048
	ds_read_b128 v[142:145], v142 offset:3072
	s_mov_b32 m0, s14
	v_lshl_add_u64 v[236:237], v[234:235], 0, v[194:195]
	s_waitcnt lgkmcnt(0)
	ds_read_b128 v[174:177], v231 offset:32768
	ds_read_b128 v[190:193], v231 offset:33792
	ds_read_b128 v[170:173], v231 offset:34816
	ds_read_b128 v[186:189], v231 offset:35840
	ds_read_b128 v[166:169], v231 offset:36864
	ds_read_b128 v[182:185], v231 offset:37888
	ds_read_b128 v[162:165], v231 offset:38912
	ds_read_b128 v[178:181], v231 offset:39936
	s_mov_b32 m0, s13
	s_nop 0
	global_load_lds_dwordx4 v196, s[98:99]
	s_mov_b32 m0, s14
	s_nop 0
	global_load_lds_dwordx4 v[236:237], off
	v_lshl_add_u64 v[234:235], v[234:235], 0, v[196:197]
	s_mov_b32 m0, s15
	s_nop 0
	global_load_lds_dwordx4 v[234:235], off
	s_waitcnt vmcnt(8)
	s_waitcnt lgkmcnt(0)
	s_barrier
	s_setprio 1
	s_waitcnt lgkmcnt(0)
	v_mfma_f32_16x16x32_bf16 v[126:129], v[146:149], v[174:177], v[126:129]
	v_mfma_f32_16x16x32_bf16 v[122:125], v[154:157], v[174:177], v[122:125]
	v_mfma_f32_16x16x32_bf16 v[118:121], v[146:149], v[170:173], v[118:121]
	v_mfma_f32_16x16x32_bf16 v[110:113], v[154:157], v[170:173], v[110:113]
	v_mfma_f32_16x16x32_bf16 v[102:105], v[146:149], v[166:169], v[102:105]
	v_mfma_f32_16x16x32_bf16 v[94:97], v[154:157], v[166:169], v[94:97]
	v_mfma_f32_16x16x32_bf16 v[86:89], v[146:149], v[162:165], v[86:89]
	v_mfma_f32_16x16x32_bf16 v[78:81], v[154:157], v[162:165], v[78:81]
	v_mfma_f32_16x16x32_bf16 v[126:129], v[150:153], v[190:193], v[126:129]
	v_mfma_f32_16x16x32_bf16 v[122:125], v[158:161], v[190:193], v[122:125]
	v_mfma_f32_16x16x32_bf16 v[118:121], v[150:153], v[186:189], v[118:121]
	v_mfma_f32_16x16x32_bf16 v[110:113], v[158:161], v[186:189], v[110:113]
	v_mfma_f32_16x16x32_bf16 v[102:105], v[150:153], v[182:185], v[102:105]
	v_mfma_f32_16x16x32_bf16 v[94:97], v[158:161], v[182:185], v[94:97]
	v_mfma_f32_16x16x32_bf16 v[86:89], v[150:153], v[178:181], v[86:89]
	v_mfma_f32_16x16x32_bf16 v[78:81], v[158:161], v[178:181], v[78:81]
	s_setprio 0
	s_setprio 1
	v_mfma_f32_16x16x32_bf16 v[114:117], v[130:133], v[174:177], v[114:117]
	v_mfma_f32_16x16x32_bf16 v[106:109], v[138:141], v[174:177], v[106:109]
	v_mfma_f32_16x16x32_bf16 v[98:101], v[130:133], v[170:173], v[98:101]
	v_mfma_f32_16x16x32_bf16 v[90:93], v[138:141], v[170:173], v[90:93]
	v_mfma_f32_16x16x32_bf16 v[82:85], v[130:133], v[166:169], v[82:85]
	v_mfma_f32_16x16x32_bf16 v[74:77], v[138:141], v[166:169], v[74:77]
	v_mfma_f32_16x16x32_bf16 v[70:73], v[130:133], v[162:165], v[70:73]
	v_mfma_f32_16x16x32_bf16 v[66:69], v[138:141], v[162:165], v[66:69]
	v_mfma_f32_16x16x32_bf16 v[114:117], v[134:137], v[190:193], v[114:117]
	v_mfma_f32_16x16x32_bf16 v[106:109], v[142:145], v[190:193], v[106:109]
	v_mfma_f32_16x16x32_bf16 v[98:101], v[134:137], v[186:189], v[98:101]
	v_mfma_f32_16x16x32_bf16 v[90:93], v[142:145], v[186:189], v[90:93]
	v_mfma_f32_16x16x32_bf16 v[82:85], v[134:137], v[182:185], v[82:85]
	v_mfma_f32_16x16x32_bf16 v[74:77], v[142:145], v[182:185], v[74:77]
	v_mfma_f32_16x16x32_bf16 v[70:73], v[134:137], v[178:181], v[70:73]
	v_mfma_f32_16x16x32_bf16 v[66:69], v[142:145], v[178:181], v[66:69]
	s_setprio 0
	s_barrier
	s_and_b64 vcc, exec, s[42:43]
	s_cbranch_vccnz .LBB0_1295
	ds_read_b128 v[174:177], v231 offset:49152
	ds_read_b128 v[190:193], v231 offset:50176
	ds_read_b128 v[170:173], v231 offset:51200
	ds_read_b128 v[186:189], v231 offset:52224
	ds_read_b128 v[166:169], v231 offset:53248
	ds_read_b128 v[182:185], v231 offset:54272
	ds_read_b128 v[162:165], v231 offset:55296
	ds_read_b128 v[178:181], v231 offset:56320
.LBB0_1295:
	s_add_u32 s58, s52, 0x40000
	s_addc_u32 s59, s53, 0
	s_add_u32 s56, s56, 0x220000
	s_addc_u32 s57, s57, 0
	s_mov_b32 m0, s16
	v_lshl_add_u64 v[234:235], s[58:59], 0, v[194:195]
	s_add_u32 s52, s52, 0x44000
	global_load_lds_dwordx4 v[234:235], off
	v_lshl_add_u64 v[234:235], s[58:59], 0, v[196:197]
	s_mov_b32 m0, s17
	s_addc_u32 s53, s53, 0
	global_load_lds_dwordx4 v[234:235], off
	v_lshl_add_u64 v[234:235], s[52:53], 0, v[194:195]
	s_mov_b32 m0, s55
	s_and_b64 vcc, exec, s[42:43]
	global_load_lds_dwordx4 v[234:235], off
	v_lshl_add_u64 v[234:235], s[52:53], 0, v[196:197]
	s_mov_b32 m0, s60
	s_nop 0
	global_load_lds_dwordx4 v[234:235], off
	v_lshl_add_u64 v[234:235], s[56:57], 0, v[194:195]
	s_mov_b32 m0, s27
	s_nop 0
	global_load_lds_dwordx4 v[234:235], off
	s_mov_b64 s[100:101], s[56:57]
	s_waitcnt vmcnt(7)
	s_waitcnt lgkmcnt(0)
	s_barrier
	s_cbranch_vccnz .LBB0_1288
	s_setprio 1
	s_waitcnt lgkmcnt(0)
	v_mfma_f32_16x16x32_bf16 v[62:65], v[146:149], v[174:177], v[62:65]
	v_mfma_f32_16x16x32_bf16 v[58:61], v[154:157], v[174:177], v[58:61]
	v_mfma_f32_16x16x32_bf16 v[46:49], v[146:149], v[170:173], v[46:49]
	v_mfma_f32_16x16x32_bf16 v[42:45], v[154:157], v[170:173], v[42:45]
	v_mfma_f32_16x16x32_bf16 v[30:33], v[146:149], v[166:169], v[30:33]
	v_mfma_f32_16x16x32_bf16 v[26:29], v[154:157], v[166:169], v[26:29]
	v_mfma_f32_16x16x32_bf16 v[14:17], v[146:149], v[162:165], v[14:17]
	v_mfma_f32_16x16x32_bf16 v[10:13], v[154:157], v[162:165], v[10:13]
	v_mfma_f32_16x16x32_bf16 v[62:65], v[150:153], v[190:193], v[62:65]
	v_mfma_f32_16x16x32_bf16 v[58:61], v[158:161], v[190:193], v[58:61]
	v_mfma_f32_16x16x32_bf16 v[46:49], v[150:153], v[186:189], v[46:49]
	v_mfma_f32_16x16x32_bf16 v[42:45], v[158:161], v[186:189], v[42:45]
	v_mfma_f32_16x16x32_bf16 v[30:33], v[150:153], v[182:185], v[30:33]
	v_mfma_f32_16x16x32_bf16 v[26:29], v[158:161], v[182:185], v[26:29]
	v_mfma_f32_16x16x32_bf16 v[14:17], v[150:153], v[178:181], v[14:17]
	v_mfma_f32_16x16x32_bf16 v[10:13], v[158:161], v[178:181], v[10:13]
	s_setprio 0
	s_setprio 1
	v_mfma_f32_16x16x32_bf16 v[54:57], v[130:133], v[174:177], v[54:57]
	v_mfma_f32_16x16x32_bf16 v[50:53], v[138:141], v[174:177], v[50:53]
	v_mfma_f32_16x16x32_bf16 v[38:41], v[130:133], v[170:173], v[38:41]
	v_mfma_f32_16x16x32_bf16 v[34:37], v[138:141], v[170:173], v[34:37]
	v_mfma_f32_16x16x32_bf16 v[22:25], v[130:133], v[166:169], v[22:25]
	v_mfma_f32_16x16x32_bf16 v[18:21], v[138:141], v[166:169], v[18:21]
	v_mfma_f32_16x16x32_bf16 v[6:9], v[130:133], v[162:165], v[6:9]
	v_mfma_f32_16x16x32_bf16 v[2:5], v[138:141], v[162:165], v[2:5]
	v_mfma_f32_16x16x32_bf16 v[54:57], v[134:137], v[190:193], v[54:57]
	v_mfma_f32_16x16x32_bf16 v[50:53], v[142:145], v[190:193], v[50:53]
	v_mfma_f32_16x16x32_bf16 v[38:41], v[134:137], v[186:189], v[38:41]
	v_mfma_f32_16x16x32_bf16 v[34:37], v[142:145], v[186:189], v[34:37]
	v_mfma_f32_16x16x32_bf16 v[22:25], v[134:137], v[182:185], v[22:25]
	v_mfma_f32_16x16x32_bf16 v[18:21], v[142:145], v[182:185], v[18:21]
	v_mfma_f32_16x16x32_bf16 v[6:9], v[134:137], v[178:181], v[6:9]
	v_mfma_f32_16x16x32_bf16 v[2:5], v[142:145], v[178:181], v[2:5]
	s_setprio 0
	s_branch .LBB0_1288

.LBB0_1612:
	v_add_u32_e32 v1, 0x10000, v232
	ds_read_b128 v[146:149], v1
	ds_read_b128 v[150:153], v1 offset:1024
	ds_read_b128 v[154:157], v1 offset:2048
	ds_read_b128 v[158:161], v1 offset:3072
	v_add_u32_e32 v1, 0x14000, v232
	ds_read_b128 v[130:133], v1
	ds_read_b128 v[134:137], v1 offset:1024
	ds_read_b128 v[138:141], v1 offset:2048
	ds_read_b128 v[142:145], v1 offset:3072
	v_lshl_add_u64 v[236:237], v[226:227], 0, s[48:49]
	s_add_i32 m0, s9, 0xc000
	s_waitcnt lgkmcnt(0)
	ds_read_b128 v[174:177], v233
	ds_read_b128 v[190:193], v233 offset:1024
	ds_read_b128 v[170:173], v233 offset:2048
	ds_read_b128 v[186:189], v233 offset:3072
	ds_read_b128 v[166:169], v233 offset:4096
	ds_read_b128 v[182:185], v233 offset:5120
	ds_read_b128 v[162:165], v233 offset:6144
	ds_read_b128 v[178:181], v233 offset:7168
	s_mov_b32 m0, s55
	s_nop 0
	global_load_lds_dwordx4 v196, s[100:101]
	s_add_i32 m0, s9, 0xc000
	s_nop 0
	global_load_lds_dwordx4 v[236:237], off
	v_lshl_add_u64 v[236:237], v[228:229], 0, s[48:49]
	s_add_i32 m0, s9, 0xe000
	s_nop 0
	global_load_lds_dwordx4 v[236:237], off
	s_waitcnt vmcnt(8)
	s_waitcnt lgkmcnt(0)
	s_barrier
	s_setprio 1
	s_waitcnt lgkmcnt(0)
	v_mfma_f32_16x16x32_bf16 v[126:129], v[146:149], v[174:177], v[126:129]
	v_mfma_f32_16x16x32_bf16 v[122:125], v[154:157], v[174:177], v[122:125]
	v_mfma_f32_16x16x32_bf16 v[118:121], v[146:149], v[170:173], v[118:121]
	v_mfma_f32_16x16x32_bf16 v[110:113], v[154:157], v[170:173], v[110:113]
	v_mfma_f32_16x16x32_bf16 v[102:105], v[146:149], v[166:169], v[102:105]
	v_mfma_f32_16x16x32_bf16 v[94:97], v[154:157], v[166:169], v[94:97]
	v_mfma_f32_16x16x32_bf16 v[86:89], v[146:149], v[162:165], v[86:89]
	v_mfma_f32_16x16x32_bf16 v[78:81], v[154:157], v[162:165], v[78:81]
	v_mfma_f32_16x16x32_bf16 v[126:129], v[150:153], v[190:193], v[126:129]
	v_mfma_f32_16x16x32_bf16 v[122:125], v[158:161], v[190:193], v[122:125]
	v_mfma_f32_16x16x32_bf16 v[118:121], v[150:153], v[186:189], v[118:121]
	v_mfma_f32_16x16x32_bf16 v[110:113], v[158:161], v[186:189], v[110:113]
	v_mfma_f32_16x16x32_bf16 v[102:105], v[150:153], v[182:185], v[102:105]
	v_mfma_f32_16x16x32_bf16 v[94:97], v[158:161], v[182:185], v[94:97]
	v_mfma_f32_16x16x32_bf16 v[86:89], v[150:153], v[178:181], v[86:89]
	v_mfma_f32_16x16x32_bf16 v[78:81], v[158:161], v[178:181], v[78:81]
	s_setprio 0
	s_setprio 1
	v_mfma_f32_16x16x32_bf16 v[114:117], v[130:133], v[174:177], v[114:117]
	v_mfma_f32_16x16x32_bf16 v[106:109], v[138:141], v[174:177], v[106:109]
	v_mfma_f32_16x16x32_bf16 v[98:101], v[130:133], v[170:173], v[98:101]
	v_mfma_f32_16x16x32_bf16 v[90:93], v[138:141], v[170:173], v[90:93]
	v_mfma_f32_16x16x32_bf16 v[82:85], v[130:133], v[166:169], v[82:85]
	v_mfma_f32_16x16x32_bf16 v[74:77], v[138:141], v[166:169], v[74:77]
	v_mfma_f32_16x16x32_bf16 v[70:73], v[130:133], v[162:165], v[70:73]
	v_mfma_f32_16x16x32_bf16 v[66:69], v[138:141], v[162:165], v[66:69]
	v_mfma_f32_16x16x32_bf16 v[114:117], v[134:137], v[190:193], v[114:117]
	v_mfma_f32_16x16x32_bf16 v[106:109], v[142:145], v[190:193], v[106:109]
	v_mfma_f32_16x16x32_bf16 v[98:101], v[134:137], v[186:189], v[98:101]
	v_mfma_f32_16x16x32_bf16 v[90:93], v[142:145], v[186:189], v[90:93]
	v_mfma_f32_16x16x32_bf16 v[82:85], v[134:137], v[182:185], v[82:85]
	v_mfma_f32_16x16x32_bf16 v[74:77], v[142:145], v[182:185], v[74:77]
	v_mfma_f32_16x16x32_bf16 v[70:73], v[134:137], v[178:181], v[70:73]
	v_mfma_f32_16x16x32_bf16 v[66:69], v[142:145], v[178:181], v[66:69]
	s_setprio 0
	s_barrier
	v_cndmask_b32_e64 v1, 0, 1, s[40:41]
	v_cmp_ne_u32_e64 s[42:43], 1, v1
	s_andn2_b64 vcc, exec, s[40:41]
	s_cbranch_vccnz .LBB0_1614
	ds_read_b128 v[174:177], v233 offset:16384
	ds_read_b128 v[190:193], v233 offset:17408
	ds_read_b128 v[170:173], v233 offset:18432
	ds_read_b128 v[186:189], v233 offset:19456
	ds_read_b128 v[166:169], v233 offset:20480
	ds_read_b128 v[182:185], v233 offset:21504
	ds_read_b128 v[162:165], v233 offset:22528
	ds_read_b128 v[178:181], v233 offset:23552
.LBB0_1614:
	s_add_u32 s50, s46, s48
	s_addc_u32 s51, s47, s49
	s_add_u32 s52, s50, 0x440000
	s_addc_u32 s53, s51, 0
	s_cmp_eq_u32 s48, 0x3fc0000
	s_cselect_b64 s[56:57], -1, 0
	s_and_b64 s[50:51], s[56:57], exec
	s_cselect_b32 s51, s31, s61
	s_cselect_b32 s50, s35, s60
	s_mov_b32 m0, s10
	s_cselect_b32 s53, s19, s53
	s_cselect_b32 s52, s20, s52
	v_lshl_add_u64 v[236:237], s[50:51], 0, v[194:195]
	s_add_u32 s68, s50, 0x4000
	global_load_lds_dwordx4 v[236:237], off
	v_lshl_add_u64 v[236:237], s[50:51], 0, v[196:197]
	s_mov_b32 m0, s11
	s_addc_u32 s69, s51, 0
	global_load_lds_dwordx4 v[236:237], off
	v_lshl_add_u64 v[236:237], s[68:69], 0, v[194:195]
	s_mov_b32 m0, s12
	s_and_b64 vcc, exec, s[42:43]
	global_load_lds_dwordx4 v[236:237], off
	v_lshl_add_u64 v[236:237], s[68:69], 0, v[196:197]
	s_mov_b32 m0, s13
	s_nop 0
	global_load_lds_dwordx4 v[236:237], off
	v_lshl_add_u64 v[236:237], s[52:53], 0, v[194:195]
	s_mov_b32 m0, s9
	s_nop 0
	global_load_lds_dwordx4 v[236:237], off
	s_mov_b64 s[98:99], s[52:53]
	s_waitcnt vmcnt(7)
	s_waitcnt lgkmcnt(0)
	s_barrier
	s_cbranch_vccnz .LBB0_1616
	s_setprio 1
	s_waitcnt lgkmcnt(0)
	v_mfma_f32_16x16x32_bf16 v[62:65], v[146:149], v[174:177], v[62:65]
	v_mfma_f32_16x16x32_bf16 v[58:61], v[154:157], v[174:177], v[58:61]
	v_mfma_f32_16x16x32_bf16 v[46:49], v[146:149], v[170:173], v[46:49]
	v_mfma_f32_16x16x32_bf16 v[42:45], v[154:157], v[170:173], v[42:45]
	v_mfma_f32_16x16x32_bf16 v[30:33], v[146:149], v[166:169], v[30:33]
	v_mfma_f32_16x16x32_bf16 v[26:29], v[154:157], v[166:169], v[26:29]
	v_mfma_f32_16x16x32_bf16 v[14:17], v[146:149], v[162:165], v[14:17]
	v_mfma_f32_16x16x32_bf16 v[10:13], v[154:157], v[162:165], v[10:13]
	v_mfma_f32_16x16x32_bf16 v[62:65], v[150:153], v[190:193], v[62:65]
	v_mfma_f32_16x16x32_bf16 v[58:61], v[158:161], v[190:193], v[58:61]
	v_mfma_f32_16x16x32_bf16 v[46:49], v[150:153], v[186:189], v[46:49]
	v_mfma_f32_16x16x32_bf16 v[42:45], v[158:161], v[186:189], v[42:45]
	v_mfma_f32_16x16x32_bf16 v[30:33], v[150:153], v[182:185], v[30:33]
	v_mfma_f32_16x16x32_bf16 v[26:29], v[158:161], v[182:185], v[26:29]
	v_mfma_f32_16x16x32_bf16 v[14:17], v[150:153], v[178:181], v[14:17]
	v_mfma_f32_16x16x32_bf16 v[10:13], v[158:161], v[178:181], v[10:13]
	s_setprio 0
	s_setprio 1
	v_mfma_f32_16x16x32_bf16 v[54:57], v[130:133], v[174:177], v[54:57]
	v_mfma_f32_16x16x32_bf16 v[50:53], v[138:141], v[174:177], v[50:53]
	v_mfma_f32_16x16x32_bf16 v[38:41], v[130:133], v[170:173], v[38:41]
	v_mfma_f32_16x16x32_bf16 v[34:37], v[138:141], v[170:173], v[34:37]
	v_mfma_f32_16x16x32_bf16 v[22:25], v[130:133], v[166:169], v[22:25]
	v_mfma_f32_16x16x32_bf16 v[18:21], v[138:141], v[166:169], v[18:21]
	v_mfma_f32_16x16x32_bf16 v[6:9], v[130:133], v[162:165], v[6:9]
	v_mfma_f32_16x16x32_bf16 v[2:5], v[138:141], v[162:165], v[2:5]
	v_mfma_f32_16x16x32_bf16 v[54:57], v[134:137], v[190:193], v[54:57]
	v_mfma_f32_16x16x32_bf16 v[50:53], v[142:145], v[190:193], v[50:53]
	v_mfma_f32_16x16x32_bf16 v[38:41], v[134:137], v[186:189], v[38:41]
	v_mfma_f32_16x16x32_bf16 v[34:37], v[142:145], v[186:189], v[34:37]
	v_mfma_f32_16x16x32_bf16 v[22:25], v[134:137], v[182:185], v[22:25]
	v_mfma_f32_16x16x32_bf16 v[18:21], v[142:145], v[182:185], v[18:21]
	v_mfma_f32_16x16x32_bf16 v[6:9], v[134:137], v[178:181], v[6:9]
	v_mfma_f32_16x16x32_bf16 v[2:5], v[142:145], v[178:181], v[2:5]
	s_setprio 0
.LBB0_1616:
	s_and_b64 vcc, s[38:39], s[56:57]
	v_cndmask_b32_e64 v131, v225, 0, vcc
	v_cndmask_b32_e32 v130, v224, v198, vcc
	v_lshl_add_u64 v[236:237], s[52:53], 0, v[130:131]
	s_barrier
	v_add_u32_e32 v1, 0x18000, v232
	ds_read_b128 v[146:149], v1
	ds_read_b128 v[150:153], v1 offset:1024
	ds_read_b128 v[154:157], v1 offset:2048
	ds_read_b128 v[158:161], v1 offset:3072
	v_add_u32_e32 v1, 0x1c000, v232
	ds_read_b128 v[130:133], v1
	ds_read_b128 v[134:137], v1 offset:1024
	ds_read_b128 v[138:141], v1 offset:2048
	ds_read_b128 v[142:145], v1 offset:3072
	s_mov_b32 m0, s15
	v_lshl_add_u64 v[238:239], v[236:237], 0, v[194:195]
	s_waitcnt lgkmcnt(0)
	ds_read_b128 v[174:177], v233 offset:32768
	ds_read_b128 v[190:193], v233 offset:33792
	ds_read_b128 v[170:173], v233 offset:34816
	ds_read_b128 v[186:189], v233 offset:35840
	ds_read_b128 v[166:169], v233 offset:36864
	ds_read_b128 v[182:185], v233 offset:37888
	ds_read_b128 v[162:165], v233 offset:38912
	ds_read_b128 v[178:181], v233 offset:39936
	s_mov_b32 m0, s14
	s_nop 0
	global_load_lds_dwordx4 v196, s[98:99]
	s_mov_b32 m0, s15
	s_nop 0
	global_load_lds_dwordx4 v[238:239], off
	v_lshl_add_u64 v[236:237], v[236:237], 0, v[196:197]
	s_mov_b32 m0, s16
	s_nop 0
	global_load_lds_dwordx4 v[236:237], off
	s_waitcnt vmcnt(8)
	s_waitcnt lgkmcnt(0)
	s_barrier
	s_setprio 1
	s_waitcnt lgkmcnt(0)
	v_mfma_f32_16x16x32_bf16 v[126:129], v[146:149], v[174:177], v[126:129]
	v_mfma_f32_16x16x32_bf16 v[122:125], v[154:157], v[174:177], v[122:125]
	v_mfma_f32_16x16x32_bf16 v[118:121], v[146:149], v[170:173], v[118:121]
	v_mfma_f32_16x16x32_bf16 v[110:113], v[154:157], v[170:173], v[110:113]
	v_mfma_f32_16x16x32_bf16 v[102:105], v[146:149], v[166:169], v[102:105]
	v_mfma_f32_16x16x32_bf16 v[94:97], v[154:157], v[166:169], v[94:97]
	v_mfma_f32_16x16x32_bf16 v[86:89], v[146:149], v[162:165], v[86:89]
	v_mfma_f32_16x16x32_bf16 v[78:81], v[154:157], v[162:165], v[78:81]
	v_mfma_f32_16x16x32_bf16 v[126:129], v[150:153], v[190:193], v[126:129]
	v_mfma_f32_16x16x32_bf16 v[122:125], v[158:161], v[190:193], v[122:125]
	v_mfma_f32_16x16x32_bf16 v[118:121], v[150:153], v[186:189], v[118:121]
	v_mfma_f32_16x16x32_bf16 v[110:113], v[158:161], v[186:189], v[110:113]
	v_mfma_f32_16x16x32_bf16 v[102:105], v[150:153], v[182:185], v[102:105]
	v_mfma_f32_16x16x32_bf16 v[94:97], v[158:161], v[182:185], v[94:97]
	v_mfma_f32_16x16x32_bf16 v[86:89], v[150:153], v[178:181], v[86:89]
	v_mfma_f32_16x16x32_bf16 v[78:81], v[158:161], v[178:181], v[78:81]
	s_setprio 0
	s_setprio 1
	v_mfma_f32_16x16x32_bf16 v[114:117], v[130:133], v[174:177], v[114:117]
	v_mfma_f32_16x16x32_bf16 v[106:109], v[138:141], v[174:177], v[106:109]
	v_mfma_f32_16x16x32_bf16 v[98:101], v[130:133], v[170:173], v[98:101]
	v_mfma_f32_16x16x32_bf16 v[90:93], v[138:141], v[170:173], v[90:93]
	v_mfma_f32_16x16x32_bf16 v[82:85], v[130:133], v[166:169], v[82:85]
	v_mfma_f32_16x16x32_bf16 v[74:77], v[138:141], v[166:169], v[74:77]
	v_mfma_f32_16x16x32_bf16 v[70:73], v[130:133], v[162:165], v[70:73]
	v_mfma_f32_16x16x32_bf16 v[66:69], v[138:141], v[162:165], v[66:69]
	v_mfma_f32_16x16x32_bf16 v[114:117], v[134:137], v[190:193], v[114:117]
	v_mfma_f32_16x16x32_bf16 v[106:109], v[142:145], v[190:193], v[106:109]
	v_mfma_f32_16x16x32_bf16 v[98:101], v[134:137], v[186:189], v[98:101]
	v_mfma_f32_16x16x32_bf16 v[90:93], v[142:145], v[186:189], v[90:93]
	v_mfma_f32_16x16x32_bf16 v[82:85], v[134:137], v[182:185], v[82:85]
	v_mfma_f32_16x16x32_bf16 v[74:77], v[142:145], v[182:185], v[74:77]
	v_mfma_f32_16x16x32_bf16 v[70:73], v[134:137], v[178:181], v[70:73]
	v_mfma_f32_16x16x32_bf16 v[66:69], v[142:145], v[178:181], v[66:69]
	s_setprio 0
	s_barrier
	s_and_b64 vcc, exec, s[42:43]
	s_cbranch_vccnz .LBB0_1618
	ds_read_b128 v[174:177], v233 offset:49152
	ds_read_b128 v[190:193], v233 offset:50176
	ds_read_b128 v[170:173], v233 offset:51200
	ds_read_b128 v[186:189], v233 offset:52224
	ds_read_b128 v[166:169], v233 offset:53248
	ds_read_b128 v[182:185], v233 offset:54272
	ds_read_b128 v[162:165], v233 offset:55296
	ds_read_b128 v[178:181], v233 offset:56320
.LBB0_1618:
	s_add_u32 s56, s50, 0x40000
	s_addc_u32 s57, s51, 0
	s_add_u32 s52, s52, 0x220000
	s_addc_u32 s53, s53, 0
	s_mov_b32 m0, s17
	v_lshl_add_u64 v[236:237], s[56:57], 0, v[194:195]
	s_add_u32 s50, s50, 0x44000
	global_load_lds_dwordx4 v[236:237], off
	v_lshl_add_u64 v[236:237], s[56:57], 0, v[196:197]
	s_mov_b32 m0, s29
	s_addc_u32 s51, s51, 0
	global_load_lds_dwordx4 v[236:237], off
	v_lshl_add_u64 v[236:237], s[50:51], 0, v[194:195]
	s_mov_b32 m0, s58
	s_and_b64 vcc, exec, s[42:43]
	global_load_lds_dwordx4 v[236:237], off
	v_lshl_add_u64 v[236:237], s[50:51], 0, v[196:197]
	s_mov_b32 m0, s59
	s_nop 0
	global_load_lds_dwordx4 v[236:237], off
	v_lshl_add_u64 v[236:237], s[52:53], 0, v[194:195]
	s_mov_b32 m0, s54
	s_nop 0
	global_load_lds_dwordx4 v[236:237], off
	s_mov_b64 s[100:101], s[52:53]
	s_waitcnt vmcnt(7)
	s_waitcnt lgkmcnt(0)
	s_barrier
	s_cbranch_vccnz .LBB0_1611
	s_setprio 1
	s_waitcnt lgkmcnt(0)
	v_mfma_f32_16x16x32_bf16 v[62:65], v[146:149], v[174:177], v[62:65]
	v_mfma_f32_16x16x32_bf16 v[58:61], v[154:157], v[174:177], v[58:61]
	v_mfma_f32_16x16x32_bf16 v[46:49], v[146:149], v[170:173], v[46:49]
	v_mfma_f32_16x16x32_bf16 v[42:45], v[154:157], v[170:173], v[42:45]
	v_mfma_f32_16x16x32_bf16 v[30:33], v[146:149], v[166:169], v[30:33]
	v_mfma_f32_16x16x32_bf16 v[26:29], v[154:157], v[166:169], v[26:29]
	v_mfma_f32_16x16x32_bf16 v[14:17], v[146:149], v[162:165], v[14:17]
	v_mfma_f32_16x16x32_bf16 v[10:13], v[154:157], v[162:165], v[10:13]
	v_mfma_f32_16x16x32_bf16 v[62:65], v[150:153], v[190:193], v[62:65]
	v_mfma_f32_16x16x32_bf16 v[58:61], v[158:161], v[190:193], v[58:61]
	v_mfma_f32_16x16x32_bf16 v[46:49], v[150:153], v[186:189], v[46:49]
	v_mfma_f32_16x16x32_bf16 v[42:45], v[158:161], v[186:189], v[42:45]
	v_mfma_f32_16x16x32_bf16 v[30:33], v[150:153], v[182:185], v[30:33]
	v_mfma_f32_16x16x32_bf16 v[26:29], v[158:161], v[182:185], v[26:29]
	v_mfma_f32_16x16x32_bf16 v[14:17], v[150:153], v[178:181], v[14:17]
	v_mfma_f32_16x16x32_bf16 v[10:13], v[158:161], v[178:181], v[10:13]
	s_setprio 0
	s_setprio 1
	v_mfma_f32_16x16x32_bf16 v[54:57], v[130:133], v[174:177], v[54:57]
	v_mfma_f32_16x16x32_bf16 v[50:53], v[138:141], v[174:177], v[50:53]
	v_mfma_f32_16x16x32_bf16 v[38:41], v[130:133], v[170:173], v[38:41]
	v_mfma_f32_16x16x32_bf16 v[34:37], v[138:141], v[170:173], v[34:37]
	v_mfma_f32_16x16x32_bf16 v[22:25], v[130:133], v[166:169], v[22:25]
	v_mfma_f32_16x16x32_bf16 v[18:21], v[138:141], v[166:169], v[18:21]
	v_mfma_f32_16x16x32_bf16 v[6:9], v[130:133], v[162:165], v[6:9]
	v_mfma_f32_16x16x32_bf16 v[2:5], v[138:141], v[162:165], v[2:5]
	v_mfma_f32_16x16x32_bf16 v[54:57], v[134:137], v[190:193], v[54:57]
	v_mfma_f32_16x16x32_bf16 v[50:53], v[142:145], v[190:193], v[50:53]
	v_mfma_f32_16x16x32_bf16 v[38:41], v[134:137], v[186:189], v[38:41]
	v_mfma_f32_16x16x32_bf16 v[34:37], v[142:145], v[186:189], v[34:37]
	v_mfma_f32_16x16x32_bf16 v[22:25], v[134:137], v[182:185], v[22:25]
	v_mfma_f32_16x16x32_bf16 v[18:21], v[142:145], v[182:185], v[18:21]
	v_mfma_f32_16x16x32_bf16 v[6:9], v[134:137], v[178:181], v[6:9]
	v_mfma_f32_16x16x32_bf16 v[2:5], v[142:145], v[178:181], v[2:5]
	s_setprio 0
	s_branch .LBB0_1611
